# v19 + the carried S(0x8000) LDS-DMA refill of each unit's first K iteration issued at the previous unit's loop exit (before its epilogue) instead of in the peeled iteration
# baseline (speedup 1.0000x reference)
.LBB0_132:
	s_and_b64 vcc, exec, s[96:97]
	s_cbranch_vccz .LBB0_137
	v_readlane_b32 s36, v249, 6
	v_readlane_b32 s37, v249, 7
	v_readlane_b32 s38, v249, 8
	v_readlane_b32 s39, v249, 9
	v_readlane_b32 s40, v249, 10
	v_readlane_b32 s41, v249, 11
	v_readlane_b32 s42, v249, 12
	v_readlane_b32 s43, v249, 13
	v_readlane_b32 s44, v249, 22
	v_readlane_b32 s45, v249, 23
	v_readlane_b32 s46, v248, 11
	v_readlane_b32 s47, v248, 12
	v_readlane_b32 s48, v248, 9
	v_readlane_b32 s49, v248, 10
	v_lshlrev_b32_e32 v1, 4, v184
	v_lshlrev_b32_e32 v22, 4, v184
	v_lshlrev_b32_e32 v2, 3, v184
	v_mov_b32_e32 v3, 0x358637bd
	s_nop 2
	global_load_dwordx4 v[6:9], v1, s[44:45] offset:0
	global_load_dwordx4 v[10:13], v1, s[44:45] offset:1024
	global_load_dwordx4 v[14:17], v1, s[44:45] offset:2048
	global_load_dwordx4 v[18:21], v1, s[44:45] offset:3072
	s_mov_b32 s0, s30
	s_mov_b32 s1, s54
	s_mov_b32 s15, s0
	s_cmp_lt_u32 s15, 0x8400
	s_cselect_b32 s12, s15, s0
	s_cmp_lt_u32 s12, 0x8000
	s_cselect_b32 s8, s36, s38
	s_cselect_b32 s9, s37, s39
	s_cselect_b32 s10, s40, s42
	s_cselect_b32 s11, s41, s43
	s_cselect_b32 s13, 0, 0x8000
	s_sub_u32 s12, s12, s13
	s_lshl_b32 s13, s12, 12
	s_add_u32 s8, s8, s13
	s_addc_u32 s9, s9, 0
	s_lshl_b32 s13, s12, 10
	s_add_u32 s10, s10, s13
	s_addc_u32 s11, s11, 0
	global_load_dwordx4 v[24:27], v1, s[8:9] offset:0
	global_load_dwordx4 v[28:31], v1, s[8:9] offset:1024
	global_load_dwordx4 v[32:35], v1, s[8:9] offset:2048
	global_load_dwordx4 v[36:39], v1, s[8:9] offset:3072
	global_load_dwordx4 v[40:43], v22, s[10:11]
	s_add_i32 s15, s15, s1
	s_cmp_lt_u32 s15, 0x8400
	s_cselect_b32 s12, s15, s0
	s_cmp_lt_u32 s12, 0x8000
	s_cselect_b32 s8, s36, s38
	s_cselect_b32 s9, s37, s39
	s_cselect_b32 s10, s40, s42
	s_cselect_b32 s11, s41, s43
	s_cselect_b32 s13, 0, 0x8000
	s_sub_u32 s12, s12, s13
	s_lshl_b32 s13, s12, 12
	s_add_u32 s8, s8, s13
	s_addc_u32 s9, s9, 0
	s_lshl_b32 s13, s12, 10
	s_add_u32 s10, s10, s13
	s_addc_u32 s11, s11, 0
	global_load_dwordx4 v[44:47], v1, s[8:9] offset:0
	global_load_dwordx4 v[48:51], v1, s[8:9] offset:1024
	global_load_dwordx4 v[52:55], v1, s[8:9] offset:2048
	global_load_dwordx4 v[56:59], v1, s[8:9] offset:3072
	global_load_dwordx4 v[60:63], v22, s[10:11]
	s_add_i32 s15, s15, s1
	s_cmp_lt_u32 s15, 0x8400
	s_cselect_b32 s12, s15, s0
	s_cmp_lt_u32 s12, 0x8000
	s_cselect_b32 s8, s36, s38
	s_cselect_b32 s9, s37, s39
	s_cselect_b32 s10, s40, s42
	s_cselect_b32 s11, s41, s43
	s_cselect_b32 s13, 0, 0x8000
	s_sub_u32 s12, s12, s13
	s_lshl_b32 s13, s12, 12
	s_add_u32 s8, s8, s13
	s_addc_u32 s9, s9, 0
	s_lshl_b32 s13, s12, 10
	s_add_u32 s10, s10, s13
	s_addc_u32 s11, s11, 0
	global_load_dwordx4 v[64:67], v1, s[8:9] offset:0
	global_load_dwordx4 v[68:71], v1, s[8:9] offset:1024
	global_load_dwordx4 v[72:75], v1, s[8:9] offset:2048
	global_load_dwordx4 v[76:79], v1, s[8:9] offset:3072
	global_load_dwordx4 v[80:83], v22, s[10:11]
	s_add_i32 s15, s15, s1
	s_cmp_lt_u32 s15, 0x8400
	s_cselect_b32 s12, s15, s0
	s_cmp_lt_u32 s12, 0x8000
	s_cselect_b32 s8, s36, s38
	s_cselect_b32 s9, s37, s39
	s_cselect_b32 s10, s40, s42
	s_cselect_b32 s11, s41, s43
	s_cselect_b32 s13, 0, 0x8000
	s_sub_u32 s12, s12, s13
	s_lshl_b32 s13, s12, 12
	s_add_u32 s8, s8, s13
	s_addc_u32 s9, s9, 0
	s_lshl_b32 s13, s12, 10
	s_add_u32 s10, s10, s13
	s_addc_u32 s11, s11, 0
	global_load_dwordx4 v[84:87], v1, s[8:9] offset:0
	global_load_dwordx4 v[88:91], v1, s[8:9] offset:1024
	global_load_dwordx4 v[92:95], v1, s[8:9] offset:2048
	global_load_dwordx4 v[96:99], v1, s[8:9] offset:3072
	global_load_dwordx4 v[100:103], v22, s[10:11]
	s_add_i32 s15, s15, s1
	s_mul_i32 s8, s1, 3
	s_add_i32 s8, s8, s0
	s_cmp_lt_u32 s8, 0x8400
	s_cbranch_scc0 .Lxn_tail
	s_mov_b32 s14, s0
	s_waitcnt vmcnt(15)
	v_mul_f32_e32 v4, v24, v24
	v_mul_f32_e32 v5, v25, v25
	v_fmac_f32_e32 v4, v26, v26
	v_fmac_f32_e32 v5, v27, v27
	v_fmac_f32_e32 v4, v28, v28
	v_fmac_f32_e32 v5, v29, v29
	v_fmac_f32_e32 v4, v30, v30
	v_fmac_f32_e32 v5, v31, v31
	v_fmac_f32_e32 v4, v32, v32
	v_fmac_f32_e32 v5, v33, v33
	v_fmac_f32_e32 v4, v34, v34
	v_fmac_f32_e32 v5, v35, v35
	v_fmac_f32_e32 v4, v36, v36
	v_fmac_f32_e32 v5, v37, v37
	v_fmac_f32_e32 v4, v38, v38
	v_fmac_f32_e32 v5, v39, v39
	v_add_f32_e32 v4, v4, v5
	v_cvt_pk_bf16_f32 v112, v40, v41
	v_cvt_pk_bf16_f32 v113, v42, v43
	v_add_f32_dpp v4, v4, v4 quad_perm:[1,0,3,2] row_mask:0xf bank_mask:0xf
	s_nop 1
	v_add_f32_dpp v4, v4, v4 quad_perm:[2,3,0,1] row_mask:0xf bank_mask:0xf
	s_nop 1
	v_add_f32_dpp v4, v4, v4 row_half_mirror row_mask:0xf bank_mask:0xf
	s_nop 1
	v_add_f32_dpp v4, v4, v4 row_mirror row_mask:0xf bank_mask:0xf
	s_nop 1
	v_readlane_b32 s28, v4, 0
	v_readlane_b32 s29, v4, 16
	v_readlane_b32 s50, v4, 32
	v_readlane_b32 s51, v4, 48
	s_lshl_b32 s13, s14, 11
	s_add_u32 s16, s46, s13
	s_addc_u32 s17, s47, 0
	s_lshl_b32 s13, s14, 9
	s_add_u32 s18, s48, s13
	s_addc_u32 s19, s49, 0
	v_mov_b32_e32 v114, s28
	v_add_f32_e32 v114, s29, v114
	v_add_f32_e32 v114, s50, v114
	v_add_f32_e32 v114, s51, v114
	v_fmamk_f32 v114, v114, 0x3a800000, v3
	v_rsq_f32_e32 v114, v114
	s_nop 0
	v_pk_mul_f32 v[116:117], v[24:25], v[114:115] op_sel_hi:[1,0]
	v_pk_mul_f32 v[118:119], v[26:27], v[114:115] op_sel_hi:[1,0]
	v_pk_mul_f32 v[120:121], v[28:29], v[114:115] op_sel_hi:[1,0]
	v_pk_mul_f32 v[122:123], v[30:31], v[114:115] op_sel_hi:[1,0]
	v_pk_mul_f32 v[124:125], v[32:33], v[114:115] op_sel_hi:[1,0]
	v_pk_mul_f32 v[126:127], v[34:35], v[114:115] op_sel_hi:[1,0]
	v_pk_mul_f32 v[128:129], v[36:37], v[114:115] op_sel_hi:[1,0]
	v_pk_mul_f32 v[130:131], v[38:39], v[114:115] op_sel_hi:[1,0]
	v_pk_mul_f32 v[116:117], v[6:7], v[116:117]
	v_pk_mul_f32 v[118:119], v[8:9], v[118:119]
	v_pk_mul_f32 v[120:121], v[10:11], v[120:121]
	v_pk_mul_f32 v[122:123], v[12:13], v[122:123]
	v_pk_mul_f32 v[124:125], v[14:15], v[124:125]
	v_pk_mul_f32 v[126:127], v[16:17], v[126:127]
	v_pk_mul_f32 v[128:129], v[18:19], v[128:129]
	v_pk_mul_f32 v[130:131], v[20:21], v[130:131]
	v_cvt_pk_bf16_f32 v104, v116, v117
	v_cvt_pk_bf16_f32 v105, v118, v119
	v_cvt_pk_bf16_f32 v106, v120, v121
	v_cvt_pk_bf16_f32 v107, v122, v123
	v_cvt_pk_bf16_f32 v108, v124, v125
	v_cvt_pk_bf16_f32 v109, v126, v127
	v_cvt_pk_bf16_f32 v110, v128, v129
	v_cvt_pk_bf16_f32 v111, v130, v131
	global_store_dwordx2 v2, v[104:105], s[16:17] offset:0
	global_store_dwordx2 v2, v[106:107], s[16:17] offset:512
	global_store_dwordx2 v2, v[108:109], s[16:17] offset:1024
	global_store_dwordx2 v2, v[110:111], s[16:17] offset:1536
	global_store_dwordx2 v2, v[112:113], s[18:19]
	s_cmp_lt_u32 s15, 0x8400
	s_cselect_b32 s12, s15, s0
	s_cmp_lt_u32 s12, 0x8000
	s_cselect_b32 s8, s36, s38
	s_cselect_b32 s9, s37, s39
	s_cselect_b32 s10, s40, s42
	s_cselect_b32 s11, s41, s43
	s_cselect_b32 s13, 0, 0x8000
	s_sub_u32 s12, s12, s13
	s_lshl_b32 s13, s12, 12
	s_add_u32 s8, s8, s13
	s_addc_u32 s9, s9, 0
	s_lshl_b32 s13, s12, 10
	s_add_u32 s10, s10, s13
	s_addc_u32 s11, s11, 0
	global_load_dwordx4 v[24:27], v1, s[8:9] offset:0
	global_load_dwordx4 v[28:31], v1, s[8:9] offset:1024
	global_load_dwordx4 v[32:35], v1, s[8:9] offset:2048
	global_load_dwordx4 v[36:39], v1, s[8:9] offset:3072
	global_load_dwordx4 v[40:43], v22, s[10:11]
	s_add_i32 s15, s15, s1
	s_add_i32 s14, s14, s1
	s_waitcnt vmcnt(20)
	v_mul_f32_e32 v4, v44, v44
	v_mul_f32_e32 v5, v45, v45
	v_fmac_f32_e32 v4, v46, v46
	v_fmac_f32_e32 v5, v47, v47
	v_fmac_f32_e32 v4, v48, v48
	v_fmac_f32_e32 v5, v49, v49
	v_fmac_f32_e32 v4, v50, v50
	v_fmac_f32_e32 v5, v51, v51
	v_fmac_f32_e32 v4, v52, v52
	v_fmac_f32_e32 v5, v53, v53
	v_fmac_f32_e32 v4, v54, v54
	v_fmac_f32_e32 v5, v55, v55
	v_fmac_f32_e32 v4, v56, v56
	v_fmac_f32_e32 v5, v57, v57
	v_fmac_f32_e32 v4, v58, v58
	v_fmac_f32_e32 v5, v59, v59
	v_add_f32_e32 v4, v4, v5
	v_cvt_pk_bf16_f32 v112, v60, v61
	v_cvt_pk_bf16_f32 v113, v62, v63
	v_add_f32_dpp v4, v4, v4 quad_perm:[1,0,3,2] row_mask:0xf bank_mask:0xf
	s_nop 1
	v_add_f32_dpp v4, v4, v4 quad_perm:[2,3,0,1] row_mask:0xf bank_mask:0xf
	s_nop 1
	v_add_f32_dpp v4, v4, v4 row_half_mirror row_mask:0xf bank_mask:0xf
	s_nop 1
	v_add_f32_dpp v4, v4, v4 row_mirror row_mask:0xf bank_mask:0xf
	s_nop 1
	v_readlane_b32 s28, v4, 0
	v_readlane_b32 s29, v4, 16
	v_readlane_b32 s50, v4, 32
	v_readlane_b32 s51, v4, 48
	s_lshl_b32 s13, s14, 11
	s_add_u32 s16, s46, s13
	s_addc_u32 s17, s47, 0
	s_lshl_b32 s13, s14, 9
	s_add_u32 s18, s48, s13
	s_addc_u32 s19, s49, 0
	v_mov_b32_e32 v114, s28
	v_add_f32_e32 v114, s29, v114
	v_add_f32_e32 v114, s50, v114
	v_add_f32_e32 v114, s51, v114
	v_fmamk_f32 v114, v114, 0x3a800000, v3
	v_rsq_f32_e32 v114, v114
	s_nop 0
	v_pk_mul_f32 v[116:117], v[44:45], v[114:115] op_sel_hi:[1,0]
	v_pk_mul_f32 v[118:119], v[46:47], v[114:115] op_sel_hi:[1,0]
	v_pk_mul_f32 v[120:121], v[48:49], v[114:115] op_sel_hi:[1,0]
	v_pk_mul_f32 v[122:123], v[50:51], v[114:115] op_sel_hi:[1,0]
	v_pk_mul_f32 v[124:125], v[52:53], v[114:115] op_sel_hi:[1,0]
	v_pk_mul_f32 v[126:127], v[54:55], v[114:115] op_sel_hi:[1,0]
	v_pk_mul_f32 v[128:129], v[56:57], v[114:115] op_sel_hi:[1,0]
	v_pk_mul_f32 v[130:131], v[58:59], v[114:115] op_sel_hi:[1,0]
	v_pk_mul_f32 v[116:117], v[6:7], v[116:117]
	v_pk_mul_f32 v[118:119], v[8:9], v[118:119]
	v_pk_mul_f32 v[120:121], v[10:11], v[120:121]
	v_pk_mul_f32 v[122:123], v[12:13], v[122:123]
	v_pk_mul_f32 v[124:125], v[14:15], v[124:125]
	v_pk_mul_f32 v[126:127], v[16:17], v[126:127]
	v_pk_mul_f32 v[128:129], v[18:19], v[128:129]
	v_pk_mul_f32 v[130:131], v[20:21], v[130:131]
	v_cvt_pk_bf16_f32 v104, v116, v117
	v_cvt_pk_bf16_f32 v105, v118, v119
	v_cvt_pk_bf16_f32 v106, v120, v121
	v_cvt_pk_bf16_f32 v107, v122, v123
	v_cvt_pk_bf16_f32 v108, v124, v125
	v_cvt_pk_bf16_f32 v109, v126, v127
	v_cvt_pk_bf16_f32 v110, v128, v129
	v_cvt_pk_bf16_f32 v111, v130, v131
	global_store_dwordx2 v2, v[104:105], s[16:17] offset:0
	global_store_dwordx2 v2, v[106:107], s[16:17] offset:512
	global_store_dwordx2 v2, v[108:109], s[16:17] offset:1024
	global_store_dwordx2 v2, v[110:111], s[16:17] offset:1536
	global_store_dwordx2 v2, v[112:113], s[18:19]
	s_cmp_lt_u32 s15, 0x8400
	s_cselect_b32 s12, s15, s0
	s_cmp_lt_u32 s12, 0x8000
	s_cselect_b32 s8, s36, s38
	s_cselect_b32 s9, s37, s39
	s_cselect_b32 s10, s40, s42
	s_cselect_b32 s11, s41, s43
	s_cselect_b32 s13, 0, 0x8000
	s_sub_u32 s12, s12, s13
	s_lshl_b32 s13, s12, 12
	s_add_u32 s8, s8, s13
	s_addc_u32 s9, s9, 0
	s_lshl_b32 s13, s12, 10
	s_add_u32 s10, s10, s13
	s_addc_u32 s11, s11, 0
	global_load_dwordx4 v[44:47], v1, s[8:9] offset:0
	global_load_dwordx4 v[48:51], v1, s[8:9] offset:1024
	global_load_dwordx4 v[52:55], v1, s[8:9] offset:2048
	global_load_dwordx4 v[56:59], v1, s[8:9] offset:3072
	global_load_dwordx4 v[60:63], v22, s[10:11]
	s_add_i32 s15, s15, s1
	s_add_i32 s14, s14, s1
	s_waitcnt vmcnt(25)
	v_mul_f32_e32 v4, v64, v64
	v_mul_f32_e32 v5, v65, v65
	v_fmac_f32_e32 v4, v66, v66
	v_fmac_f32_e32 v5, v67, v67
	v_fmac_f32_e32 v4, v68, v68
	v_fmac_f32_e32 v5, v69, v69
	v_fmac_f32_e32 v4, v70, v70
	v_fmac_f32_e32 v5, v71, v71
	v_fmac_f32_e32 v4, v72, v72
	v_fmac_f32_e32 v5, v73, v73
	v_fmac_f32_e32 v4, v74, v74
	v_fmac_f32_e32 v5, v75, v75
	v_fmac_f32_e32 v4, v76, v76
	v_fmac_f32_e32 v5, v77, v77
	v_fmac_f32_e32 v4, v78, v78
	v_fmac_f32_e32 v5, v79, v79
	v_add_f32_e32 v4, v4, v5
	v_cvt_pk_bf16_f32 v112, v80, v81
	v_cvt_pk_bf16_f32 v113, v82, v83
	v_add_f32_dpp v4, v4, v4 quad_perm:[1,0,3,2] row_mask:0xf bank_mask:0xf
	s_nop 1
	v_add_f32_dpp v4, v4, v4 quad_perm:[2,3,0,1] row_mask:0xf bank_mask:0xf
	s_nop 1
	v_add_f32_dpp v4, v4, v4 row_half_mirror row_mask:0xf bank_mask:0xf
	s_nop 1
	v_add_f32_dpp v4, v4, v4 row_mirror row_mask:0xf bank_mask:0xf
	s_nop 1
	v_readlane_b32 s28, v4, 0
	v_readlane_b32 s29, v4, 16
	v_readlane_b32 s50, v4, 32
	v_readlane_b32 s51, v4, 48
	s_lshl_b32 s13, s14, 11
	s_add_u32 s16, s46, s13
	s_addc_u32 s17, s47, 0
	s_lshl_b32 s13, s14, 9
	s_add_u32 s18, s48, s13
	s_addc_u32 s19, s49, 0
	v_mov_b32_e32 v114, s28
	v_add_f32_e32 v114, s29, v114
	v_add_f32_e32 v114, s50, v114
	v_add_f32_e32 v114, s51, v114
	v_fmamk_f32 v114, v114, 0x3a800000, v3
	v_rsq_f32_e32 v114, v114
	s_nop 0
	v_pk_mul_f32 v[116:117], v[64:65], v[114:115] op_sel_hi:[1,0]
	v_pk_mul_f32 v[118:119], v[66:67], v[114:115] op_sel_hi:[1,0]
	v_pk_mul_f32 v[120:121], v[68:69], v[114:115] op_sel_hi:[1,0]
	v_pk_mul_f32 v[122:123], v[70:71], v[114:115] op_sel_hi:[1,0]
	v_pk_mul_f32 v[124:125], v[72:73], v[114:115] op_sel_hi:[1,0]
	v_pk_mul_f32 v[126:127], v[74:75], v[114:115] op_sel_hi:[1,0]
	v_pk_mul_f32 v[128:129], v[76:77], v[114:115] op_sel_hi:[1,0]
	v_pk_mul_f32 v[130:131], v[78:79], v[114:115] op_sel_hi:[1,0]
	v_pk_mul_f32 v[116:117], v[6:7], v[116:117]
	v_pk_mul_f32 v[118:119], v[8:9], v[118:119]
	v_pk_mul_f32 v[120:121], v[10:11], v[120:121]
	v_pk_mul_f32 v[122:123], v[12:13], v[122:123]
	v_pk_mul_f32 v[124:125], v[14:15], v[124:125]
	v_pk_mul_f32 v[126:127], v[16:17], v[126:127]
	v_pk_mul_f32 v[128:129], v[18:19], v[128:129]
	v_pk_mul_f32 v[130:131], v[20:21], v[130:131]
	v_cvt_pk_bf16_f32 v104, v116, v117
	v_cvt_pk_bf16_f32 v105, v118, v119
	v_cvt_pk_bf16_f32 v106, v120, v121
	v_cvt_pk_bf16_f32 v107, v122, v123
	v_cvt_pk_bf16_f32 v108, v124, v125
	v_cvt_pk_bf16_f32 v109, v126, v127
	v_cvt_pk_bf16_f32 v110, v128, v129
	v_cvt_pk_bf16_f32 v111, v130, v131
	global_store_dwordx2 v2, v[104:105], s[16:17] offset:0
	global_store_dwordx2 v2, v[106:107], s[16:17] offset:512
	global_store_dwordx2 v2, v[108:109], s[16:17] offset:1024
	global_store_dwordx2 v2, v[110:111], s[16:17] offset:1536
	global_store_dwordx2 v2, v[112:113], s[18:19]
	s_cmp_lt_u32 s15, 0x8400
	s_cselect_b32 s12, s15, s0
	s_cmp_lt_u32 s12, 0x8000
	s_cselect_b32 s8, s36, s38
	s_cselect_b32 s9, s37, s39
	s_cselect_b32 s10, s40, s42
	s_cselect_b32 s11, s41, s43
	s_cselect_b32 s13, 0, 0x8000
	s_sub_u32 s12, s12, s13
	s_lshl_b32 s13, s12, 12
	s_add_u32 s8, s8, s13
	s_addc_u32 s9, s9, 0
	s_lshl_b32 s13, s12, 10
	s_add_u32 s10, s10, s13
	s_addc_u32 s11, s11, 0
	global_load_dwordx4 v[64:67], v1, s[8:9] offset:0
	global_load_dwordx4 v[68:71], v1, s[8:9] offset:1024
	global_load_dwordx4 v[72:75], v1, s[8:9] offset:2048
	global_load_dwordx4 v[76:79], v1, s[8:9] offset:3072
	global_load_dwordx4 v[80:83], v22, s[10:11]
	s_add_i32 s15, s15, s1
	s_add_i32 s14, s14, s1
	s_waitcnt vmcnt(30)
	v_mul_f32_e32 v4, v84, v84
	v_mul_f32_e32 v5, v85, v85
	v_fmac_f32_e32 v4, v86, v86
	v_fmac_f32_e32 v5, v87, v87
	v_fmac_f32_e32 v4, v88, v88
	v_fmac_f32_e32 v5, v89, v89
	v_fmac_f32_e32 v4, v90, v90
	v_fmac_f32_e32 v5, v91, v91
	v_fmac_f32_e32 v4, v92, v92
	v_fmac_f32_e32 v5, v93, v93
	v_fmac_f32_e32 v4, v94, v94
	v_fmac_f32_e32 v5, v95, v95
	v_fmac_f32_e32 v4, v96, v96
	v_fmac_f32_e32 v5, v97, v97
	v_fmac_f32_e32 v4, v98, v98
	v_fmac_f32_e32 v5, v99, v99
	v_add_f32_e32 v4, v4, v5
	v_cvt_pk_bf16_f32 v112, v100, v101
	v_cvt_pk_bf16_f32 v113, v102, v103
	v_add_f32_dpp v4, v4, v4 quad_perm:[1,0,3,2] row_mask:0xf bank_mask:0xf
	s_nop 1
	v_add_f32_dpp v4, v4, v4 quad_perm:[2,3,0,1] row_mask:0xf bank_mask:0xf
	s_nop 1
	v_add_f32_dpp v4, v4, v4 row_half_mirror row_mask:0xf bank_mask:0xf
	s_nop 1
	v_add_f32_dpp v4, v4, v4 row_mirror row_mask:0xf bank_mask:0xf
	s_nop 1
	v_readlane_b32 s28, v4, 0
	v_readlane_b32 s29, v4, 16
	v_readlane_b32 s50, v4, 32
	v_readlane_b32 s51, v4, 48
	s_lshl_b32 s13, s14, 11
	s_add_u32 s16, s46, s13
	s_addc_u32 s17, s47, 0
	s_lshl_b32 s13, s14, 9
	s_add_u32 s18, s48, s13
	s_addc_u32 s19, s49, 0
	v_mov_b32_e32 v114, s28
	v_add_f32_e32 v114, s29, v114
	v_add_f32_e32 v114, s50, v114
	v_add_f32_e32 v114, s51, v114
	v_fmamk_f32 v114, v114, 0x3a800000, v3
	v_rsq_f32_e32 v114, v114
	s_nop 0
	v_pk_mul_f32 v[116:117], v[84:85], v[114:115] op_sel_hi:[1,0]
	v_pk_mul_f32 v[118:119], v[86:87], v[114:115] op_sel_hi:[1,0]
	v_pk_mul_f32 v[120:121], v[88:89], v[114:115] op_sel_hi:[1,0]
	v_pk_mul_f32 v[122:123], v[90:91], v[114:115] op_sel_hi:[1,0]
	v_pk_mul_f32 v[124:125], v[92:93], v[114:115] op_sel_hi:[1,0]
	v_pk_mul_f32 v[126:127], v[94:95], v[114:115] op_sel_hi:[1,0]
	v_pk_mul_f32 v[128:129], v[96:97], v[114:115] op_sel_hi:[1,0]
	v_pk_mul_f32 v[130:131], v[98:99], v[114:115] op_sel_hi:[1,0]
	v_pk_mul_f32 v[116:117], v[6:7], v[116:117]
	v_pk_mul_f32 v[118:119], v[8:9], v[118:119]
	v_pk_mul_f32 v[120:121], v[10:11], v[120:121]
	v_pk_mul_f32 v[122:123], v[12:13], v[122:123]
	v_pk_mul_f32 v[124:125], v[14:15], v[124:125]
	v_pk_mul_f32 v[126:127], v[16:17], v[126:127]
	v_pk_mul_f32 v[128:129], v[18:19], v[128:129]
	v_pk_mul_f32 v[130:131], v[20:21], v[130:131]
	v_cvt_pk_bf16_f32 v104, v116, v117
	v_cvt_pk_bf16_f32 v105, v118, v119
	v_cvt_pk_bf16_f32 v106, v120, v121
	v_cvt_pk_bf16_f32 v107, v122, v123
	v_cvt_pk_bf16_f32 v108, v124, v125
	v_cvt_pk_bf16_f32 v109, v126, v127
	v_cvt_pk_bf16_f32 v110, v128, v129
	v_cvt_pk_bf16_f32 v111, v130, v131
	global_store_dwordx2 v2, v[104:105], s[16:17] offset:0
	global_store_dwordx2 v2, v[106:107], s[16:17] offset:512
	global_store_dwordx2 v2, v[108:109], s[16:17] offset:1024
	global_store_dwordx2 v2, v[110:111], s[16:17] offset:1536
	global_store_dwordx2 v2, v[112:113], s[18:19]
	s_cmp_lt_u32 s15, 0x8400
	s_cselect_b32 s12, s15, s0
	s_cmp_lt_u32 s12, 0x8000
	s_cselect_b32 s8, s36, s38
	s_cselect_b32 s9, s37, s39
	s_cselect_b32 s10, s40, s42
	s_cselect_b32 s11, s41, s43
	s_cselect_b32 s13, 0, 0x8000
	s_sub_u32 s12, s12, s13
	s_lshl_b32 s13, s12, 12
	s_add_u32 s8, s8, s13
	s_addc_u32 s9, s9, 0
	s_lshl_b32 s13, s12, 10
	s_add_u32 s10, s10, s13
	s_addc_u32 s11, s11, 0
	global_load_dwordx4 v[84:87], v1, s[8:9] offset:0
	global_load_dwordx4 v[88:91], v1, s[8:9] offset:1024
	global_load_dwordx4 v[92:95], v1, s[8:9] offset:2048
	global_load_dwordx4 v[96:99], v1, s[8:9] offset:3072
	global_load_dwordx4 v[100:103], v22, s[10:11]
	s_add_i32 s15, s15, s1
	s_add_i32 s14, s14, s1
	s_mov_b32 s0, s14
.Lxn_loop:
	s_mul_i32 s8, s1, 3
	s_add_i32 s8, s8, s0
	s_cmp_lt_u32 s8, 0x8400
	s_cbranch_scc0 .Lxn_tail
	s_waitcnt vmcnt(30)
	v_mul_f32_e32 v4, v24, v24
	v_mul_f32_e32 v5, v25, v25
	v_fmac_f32_e32 v4, v26, v26
	v_fmac_f32_e32 v5, v27, v27
	v_fmac_f32_e32 v4, v28, v28
	v_fmac_f32_e32 v5, v29, v29
	v_fmac_f32_e32 v4, v30, v30
	v_fmac_f32_e32 v5, v31, v31
	v_fmac_f32_e32 v4, v32, v32
	v_fmac_f32_e32 v5, v33, v33
	v_fmac_f32_e32 v4, v34, v34
	v_fmac_f32_e32 v5, v35, v35
	v_fmac_f32_e32 v4, v36, v36
	v_fmac_f32_e32 v5, v37, v37
	v_fmac_f32_e32 v4, v38, v38
	v_fmac_f32_e32 v5, v39, v39
	v_add_f32_e32 v4, v4, v5
	v_cvt_pk_bf16_f32 v112, v40, v41
	v_cvt_pk_bf16_f32 v113, v42, v43
	v_add_f32_dpp v4, v4, v4 quad_perm:[1,0,3,2] row_mask:0xf bank_mask:0xf
	s_nop 1
	v_add_f32_dpp v4, v4, v4 quad_perm:[2,3,0,1] row_mask:0xf bank_mask:0xf
	s_nop 1
	v_add_f32_dpp v4, v4, v4 row_half_mirror row_mask:0xf bank_mask:0xf
	s_nop 1
	v_add_f32_dpp v4, v4, v4 row_mirror row_mask:0xf bank_mask:0xf
	s_nop 1
	v_readlane_b32 s28, v4, 0
	v_readlane_b32 s29, v4, 16
	v_readlane_b32 s50, v4, 32
	v_readlane_b32 s51, v4, 48
	s_lshl_b32 s13, s14, 11
	s_add_u32 s16, s46, s13
	s_addc_u32 s17, s47, 0
	s_lshl_b32 s13, s14, 9
	s_add_u32 s18, s48, s13
	s_addc_u32 s19, s49, 0
	v_mov_b32_e32 v114, s28
	v_add_f32_e32 v114, s29, v114
	v_add_f32_e32 v114, s50, v114
	v_add_f32_e32 v114, s51, v114
	v_fmamk_f32 v114, v114, 0x3a800000, v3
	v_rsq_f32_e32 v114, v114
	s_nop 0
	v_pk_mul_f32 v[116:117], v[24:25], v[114:115] op_sel_hi:[1,0]
	v_pk_mul_f32 v[118:119], v[26:27], v[114:115] op_sel_hi:[1,0]
	v_pk_mul_f32 v[120:121], v[28:29], v[114:115] op_sel_hi:[1,0]
	v_pk_mul_f32 v[122:123], v[30:31], v[114:115] op_sel_hi:[1,0]
	v_pk_mul_f32 v[124:125], v[32:33], v[114:115] op_sel_hi:[1,0]
	v_pk_mul_f32 v[126:127], v[34:35], v[114:115] op_sel_hi:[1,0]
	v_pk_mul_f32 v[128:129], v[36:37], v[114:115] op_sel_hi:[1,0]
	v_pk_mul_f32 v[130:131], v[38:39], v[114:115] op_sel_hi:[1,0]
	v_pk_mul_f32 v[116:117], v[6:7], v[116:117]
	v_pk_mul_f32 v[118:119], v[8:9], v[118:119]
	v_pk_mul_f32 v[120:121], v[10:11], v[120:121]
	v_pk_mul_f32 v[122:123], v[12:13], v[122:123]
	v_pk_mul_f32 v[124:125], v[14:15], v[124:125]
	v_pk_mul_f32 v[126:127], v[16:17], v[126:127]
	v_pk_mul_f32 v[128:129], v[18:19], v[128:129]
	v_pk_mul_f32 v[130:131], v[20:21], v[130:131]
	v_cvt_pk_bf16_f32 v104, v116, v117
	v_cvt_pk_bf16_f32 v105, v118, v119
	v_cvt_pk_bf16_f32 v106, v120, v121
	v_cvt_pk_bf16_f32 v107, v122, v123
	v_cvt_pk_bf16_f32 v108, v124, v125
	v_cvt_pk_bf16_f32 v109, v126, v127
	v_cvt_pk_bf16_f32 v110, v128, v129
	v_cvt_pk_bf16_f32 v111, v130, v131
	global_store_dwordx2 v2, v[104:105], s[16:17] offset:0
	global_store_dwordx2 v2, v[106:107], s[16:17] offset:512
	global_store_dwordx2 v2, v[108:109], s[16:17] offset:1024
	global_store_dwordx2 v2, v[110:111], s[16:17] offset:1536
	global_store_dwordx2 v2, v[112:113], s[18:19]
	s_cmp_lt_u32 s15, 0x8400
	s_cselect_b32 s12, s15, s0
	s_cmp_lt_u32 s12, 0x8000
	s_cselect_b32 s8, s36, s38
	s_cselect_b32 s9, s37, s39
	s_cselect_b32 s10, s40, s42
	s_cselect_b32 s11, s41, s43
	s_cselect_b32 s13, 0, 0x8000
	s_sub_u32 s12, s12, s13
	s_lshl_b32 s13, s12, 12
	s_add_u32 s8, s8, s13
	s_addc_u32 s9, s9, 0
	s_lshl_b32 s13, s12, 10
	s_add_u32 s10, s10, s13
	s_addc_u32 s11, s11, 0
	global_load_dwordx4 v[24:27], v1, s[8:9] offset:0
	global_load_dwordx4 v[28:31], v1, s[8:9] offset:1024
	global_load_dwordx4 v[32:35], v1, s[8:9] offset:2048
	global_load_dwordx4 v[36:39], v1, s[8:9] offset:3072
	global_load_dwordx4 v[40:43], v22, s[10:11]
	s_add_i32 s15, s15, s1
	s_add_i32 s14, s14, s1
	s_waitcnt vmcnt(30)
	v_mul_f32_e32 v4, v44, v44
	v_mul_f32_e32 v5, v45, v45
	v_fmac_f32_e32 v4, v46, v46
	v_fmac_f32_e32 v5, v47, v47
	v_fmac_f32_e32 v4, v48, v48
	v_fmac_f32_e32 v5, v49, v49
	v_fmac_f32_e32 v4, v50, v50
	v_fmac_f32_e32 v5, v51, v51
	v_fmac_f32_e32 v4, v52, v52
	v_fmac_f32_e32 v5, v53, v53
	v_fmac_f32_e32 v4, v54, v54
	v_fmac_f32_e32 v5, v55, v55
	v_fmac_f32_e32 v4, v56, v56
	v_fmac_f32_e32 v5, v57, v57
	v_fmac_f32_e32 v4, v58, v58
	v_fmac_f32_e32 v5, v59, v59
	v_add_f32_e32 v4, v4, v5
	v_cvt_pk_bf16_f32 v112, v60, v61
	v_cvt_pk_bf16_f32 v113, v62, v63
	v_add_f32_dpp v4, v4, v4 quad_perm:[1,0,3,2] row_mask:0xf bank_mask:0xf
	s_nop 1
	v_add_f32_dpp v4, v4, v4 quad_perm:[2,3,0,1] row_mask:0xf bank_mask:0xf
	s_nop 1
	v_add_f32_dpp v4, v4, v4 row_half_mirror row_mask:0xf bank_mask:0xf
	s_nop 1
	v_add_f32_dpp v4, v4, v4 row_mirror row_mask:0xf bank_mask:0xf
	s_nop 1
	v_readlane_b32 s28, v4, 0
	v_readlane_b32 s29, v4, 16
	v_readlane_b32 s50, v4, 32
	v_readlane_b32 s51, v4, 48
	s_lshl_b32 s13, s14, 11
	s_add_u32 s16, s46, s13
	s_addc_u32 s17, s47, 0
	s_lshl_b32 s13, s14, 9
	s_add_u32 s18, s48, s13
	s_addc_u32 s19, s49, 0
	v_mov_b32_e32 v114, s28
	v_add_f32_e32 v114, s29, v114
	v_add_f32_e32 v114, s50, v114
	v_add_f32_e32 v114, s51, v114
	v_fmamk_f32 v114, v114, 0x3a800000, v3
	v_rsq_f32_e32 v114, v114
	s_nop 0
	v_pk_mul_f32 v[116:117], v[44:45], v[114:115] op_sel_hi:[1,0]
	v_pk_mul_f32 v[118:119], v[46:47], v[114:115] op_sel_hi:[1,0]
	v_pk_mul_f32 v[120:121], v[48:49], v[114:115] op_sel_hi:[1,0]
	v_pk_mul_f32 v[122:123], v[50:51], v[114:115] op_sel_hi:[1,0]
	v_pk_mul_f32 v[124:125], v[52:53], v[114:115] op_sel_hi:[1,0]
	v_pk_mul_f32 v[126:127], v[54:55], v[114:115] op_sel_hi:[1,0]
	v_pk_mul_f32 v[128:129], v[56:57], v[114:115] op_sel_hi:[1,0]
	v_pk_mul_f32 v[130:131], v[58:59], v[114:115] op_sel_hi:[1,0]
	v_pk_mul_f32 v[116:117], v[6:7], v[116:117]
	v_pk_mul_f32 v[118:119], v[8:9], v[118:119]
	v_pk_mul_f32 v[120:121], v[10:11], v[120:121]
	v_pk_mul_f32 v[122:123], v[12:13], v[122:123]
	v_pk_mul_f32 v[124:125], v[14:15], v[124:125]
	v_pk_mul_f32 v[126:127], v[16:17], v[126:127]
	v_pk_mul_f32 v[128:129], v[18:19], v[128:129]
	v_pk_mul_f32 v[130:131], v[20:21], v[130:131]
	v_cvt_pk_bf16_f32 v104, v116, v117
	v_cvt_pk_bf16_f32 v105, v118, v119
	v_cvt_pk_bf16_f32 v106, v120, v121
	v_cvt_pk_bf16_f32 v107, v122, v123
	v_cvt_pk_bf16_f32 v108, v124, v125
	v_cvt_pk_bf16_f32 v109, v126, v127
	v_cvt_pk_bf16_f32 v110, v128, v129
	v_cvt_pk_bf16_f32 v111, v130, v131
	global_store_dwordx2 v2, v[104:105], s[16:17] offset:0
	global_store_dwordx2 v2, v[106:107], s[16:17] offset:512
	global_store_dwordx2 v2, v[108:109], s[16:17] offset:1024
	global_store_dwordx2 v2, v[110:111], s[16:17] offset:1536
	global_store_dwordx2 v2, v[112:113], s[18:19]
	s_cmp_lt_u32 s15, 0x8400
	s_cselect_b32 s12, s15, s0
	s_cmp_lt_u32 s12, 0x8000
	s_cselect_b32 s8, s36, s38
	s_cselect_b32 s9, s37, s39
	s_cselect_b32 s10, s40, s42
	s_cselect_b32 s11, s41, s43
	s_cselect_b32 s13, 0, 0x8000
	s_sub_u32 s12, s12, s13
	s_lshl_b32 s13, s12, 12
	s_add_u32 s8, s8, s13
	s_addc_u32 s9, s9, 0
	s_lshl_b32 s13, s12, 10
	s_add_u32 s10, s10, s13
	s_addc_u32 s11, s11, 0
	global_load_dwordx4 v[44:47], v1, s[8:9] offset:0
	global_load_dwordx4 v[48:51], v1, s[8:9] offset:1024
	global_load_dwordx4 v[52:55], v1, s[8:9] offset:2048
	global_load_dwordx4 v[56:59], v1, s[8:9] offset:3072
	global_load_dwordx4 v[60:63], v22, s[10:11]
	s_add_i32 s15, s15, s1
	s_add_i32 s14, s14, s1
	s_waitcnt vmcnt(30)
	v_mul_f32_e32 v4, v64, v64
	v_mul_f32_e32 v5, v65, v65
	v_fmac_f32_e32 v4, v66, v66
	v_fmac_f32_e32 v5, v67, v67
	v_fmac_f32_e32 v4, v68, v68
	v_fmac_f32_e32 v5, v69, v69
	v_fmac_f32_e32 v4, v70, v70
	v_fmac_f32_e32 v5, v71, v71
	v_fmac_f32_e32 v4, v72, v72
	v_fmac_f32_e32 v5, v73, v73
	v_fmac_f32_e32 v4, v74, v74
	v_fmac_f32_e32 v5, v75, v75
	v_fmac_f32_e32 v4, v76, v76
	v_fmac_f32_e32 v5, v77, v77
	v_fmac_f32_e32 v4, v78, v78
	v_fmac_f32_e32 v5, v79, v79
	v_add_f32_e32 v4, v4, v5
	v_cvt_pk_bf16_f32 v112, v80, v81
	v_cvt_pk_bf16_f32 v113, v82, v83
	v_add_f32_dpp v4, v4, v4 quad_perm:[1,0,3,2] row_mask:0xf bank_mask:0xf
	s_nop 1
	v_add_f32_dpp v4, v4, v4 quad_perm:[2,3,0,1] row_mask:0xf bank_mask:0xf
	s_nop 1
	v_add_f32_dpp v4, v4, v4 row_half_mirror row_mask:0xf bank_mask:0xf
	s_nop 1
	v_add_f32_dpp v4, v4, v4 row_mirror row_mask:0xf bank_mask:0xf
	s_nop 1
	v_readlane_b32 s28, v4, 0
	v_readlane_b32 s29, v4, 16
	v_readlane_b32 s50, v4, 32
	v_readlane_b32 s51, v4, 48
	s_lshl_b32 s13, s14, 11
	s_add_u32 s16, s46, s13
	s_addc_u32 s17, s47, 0
	s_lshl_b32 s13, s14, 9
	s_add_u32 s18, s48, s13
	s_addc_u32 s19, s49, 0
	v_mov_b32_e32 v114, s28
	v_add_f32_e32 v114, s29, v114
	v_add_f32_e32 v114, s50, v114
	v_add_f32_e32 v114, s51, v114
	v_fmamk_f32 v114, v114, 0x3a800000, v3
	v_rsq_f32_e32 v114, v114
	s_nop 0
	v_pk_mul_f32 v[116:117], v[64:65], v[114:115] op_sel_hi:[1,0]
	v_pk_mul_f32 v[118:119], v[66:67], v[114:115] op_sel_hi:[1,0]
	v_pk_mul_f32 v[120:121], v[68:69], v[114:115] op_sel_hi:[1,0]
	v_pk_mul_f32 v[122:123], v[70:71], v[114:115] op_sel_hi:[1,0]
	v_pk_mul_f32 v[124:125], v[72:73], v[114:115] op_sel_hi:[1,0]
	v_pk_mul_f32 v[126:127], v[74:75], v[114:115] op_sel_hi:[1,0]
	v_pk_mul_f32 v[128:129], v[76:77], v[114:115] op_sel_hi:[1,0]
	v_pk_mul_f32 v[130:131], v[78:79], v[114:115] op_sel_hi:[1,0]
	v_pk_mul_f32 v[116:117], v[6:7], v[116:117]
	v_pk_mul_f32 v[118:119], v[8:9], v[118:119]
	v_pk_mul_f32 v[120:121], v[10:11], v[120:121]
	v_pk_mul_f32 v[122:123], v[12:13], v[122:123]
	v_pk_mul_f32 v[124:125], v[14:15], v[124:125]
	v_pk_mul_f32 v[126:127], v[16:17], v[126:127]
	v_pk_mul_f32 v[128:129], v[18:19], v[128:129]
	v_pk_mul_f32 v[130:131], v[20:21], v[130:131]
	v_cvt_pk_bf16_f32 v104, v116, v117
	v_cvt_pk_bf16_f32 v105, v118, v119
	v_cvt_pk_bf16_f32 v106, v120, v121
	v_cvt_pk_bf16_f32 v107, v122, v123
	v_cvt_pk_bf16_f32 v108, v124, v125
	v_cvt_pk_bf16_f32 v109, v126, v127
	v_cvt_pk_bf16_f32 v110, v128, v129
	v_cvt_pk_bf16_f32 v111, v130, v131
	global_store_dwordx2 v2, v[104:105], s[16:17] offset:0
	global_store_dwordx2 v2, v[106:107], s[16:17] offset:512
	global_store_dwordx2 v2, v[108:109], s[16:17] offset:1024
	global_store_dwordx2 v2, v[110:111], s[16:17] offset:1536
	global_store_dwordx2 v2, v[112:113], s[18:19]
	s_cmp_lt_u32 s15, 0x8400
	s_cselect_b32 s12, s15, s0
	s_cmp_lt_u32 s12, 0x8000
	s_cselect_b32 s8, s36, s38
	s_cselect_b32 s9, s37, s39
	s_cselect_b32 s10, s40, s42
	s_cselect_b32 s11, s41, s43
	s_cselect_b32 s13, 0, 0x8000
	s_sub_u32 s12, s12, s13
	s_lshl_b32 s13, s12, 12
	s_add_u32 s8, s8, s13
	s_addc_u32 s9, s9, 0
	s_lshl_b32 s13, s12, 10
	s_add_u32 s10, s10, s13
	s_addc_u32 s11, s11, 0
	global_load_dwordx4 v[64:67], v1, s[8:9] offset:0
	global_load_dwordx4 v[68:71], v1, s[8:9] offset:1024
	global_load_dwordx4 v[72:75], v1, s[8:9] offset:2048
	global_load_dwordx4 v[76:79], v1, s[8:9] offset:3072
	global_load_dwordx4 v[80:83], v22, s[10:11]
	s_add_i32 s15, s15, s1
	s_add_i32 s14, s14, s1
	s_waitcnt vmcnt(30)
	v_mul_f32_e32 v4, v84, v84
	v_mul_f32_e32 v5, v85, v85
	v_fmac_f32_e32 v4, v86, v86
	v_fmac_f32_e32 v5, v87, v87
	v_fmac_f32_e32 v4, v88, v88
	v_fmac_f32_e32 v5, v89, v89
	v_fmac_f32_e32 v4, v90, v90
	v_fmac_f32_e32 v5, v91, v91
	v_fmac_f32_e32 v4, v92, v92
	v_fmac_f32_e32 v5, v93, v93
	v_fmac_f32_e32 v4, v94, v94
	v_fmac_f32_e32 v5, v95, v95
	v_fmac_f32_e32 v4, v96, v96
	v_fmac_f32_e32 v5, v97, v97
	v_fmac_f32_e32 v4, v98, v98
	v_fmac_f32_e32 v5, v99, v99
	v_add_f32_e32 v4, v4, v5
	v_cvt_pk_bf16_f32 v112, v100, v101
	v_cvt_pk_bf16_f32 v113, v102, v103
	v_add_f32_dpp v4, v4, v4 quad_perm:[1,0,3,2] row_mask:0xf bank_mask:0xf
	s_nop 1
	v_add_f32_dpp v4, v4, v4 quad_perm:[2,3,0,1] row_mask:0xf bank_mask:0xf
	s_nop 1
	v_add_f32_dpp v4, v4, v4 row_half_mirror row_mask:0xf bank_mask:0xf
	s_nop 1
	v_add_f32_dpp v4, v4, v4 row_mirror row_mask:0xf bank_mask:0xf
	s_nop 1
	v_readlane_b32 s28, v4, 0
	v_readlane_b32 s29, v4, 16
	v_readlane_b32 s50, v4, 32
	v_readlane_b32 s51, v4, 48
	s_lshl_b32 s13, s14, 11
	s_add_u32 s16, s46, s13
	s_addc_u32 s17, s47, 0
	s_lshl_b32 s13, s14, 9
	s_add_u32 s18, s48, s13
	s_addc_u32 s19, s49, 0
	v_mov_b32_e32 v114, s28
	v_add_f32_e32 v114, s29, v114
	v_add_f32_e32 v114, s50, v114
	v_add_f32_e32 v114, s51, v114
	v_fmamk_f32 v114, v114, 0x3a800000, v3
	v_rsq_f32_e32 v114, v114
	s_nop 0
	v_pk_mul_f32 v[116:117], v[84:85], v[114:115] op_sel_hi:[1,0]
	v_pk_mul_f32 v[118:119], v[86:87], v[114:115] op_sel_hi:[1,0]
	v_pk_mul_f32 v[120:121], v[88:89], v[114:115] op_sel_hi:[1,0]
	v_pk_mul_f32 v[122:123], v[90:91], v[114:115] op_sel_hi:[1,0]
	v_pk_mul_f32 v[124:125], v[92:93], v[114:115] op_sel_hi:[1,0]
	v_pk_mul_f32 v[126:127], v[94:95], v[114:115] op_sel_hi:[1,0]
	v_pk_mul_f32 v[128:129], v[96:97], v[114:115] op_sel_hi:[1,0]
	v_pk_mul_f32 v[130:131], v[98:99], v[114:115] op_sel_hi:[1,0]
	v_pk_mul_f32 v[116:117], v[6:7], v[116:117]
	v_pk_mul_f32 v[118:119], v[8:9], v[118:119]
	v_pk_mul_f32 v[120:121], v[10:11], v[120:121]
	v_pk_mul_f32 v[122:123], v[12:13], v[122:123]
	v_pk_mul_f32 v[124:125], v[14:15], v[124:125]
	v_pk_mul_f32 v[126:127], v[16:17], v[126:127]
	v_pk_mul_f32 v[128:129], v[18:19], v[128:129]
	v_pk_mul_f32 v[130:131], v[20:21], v[130:131]
	v_cvt_pk_bf16_f32 v104, v116, v117
	v_cvt_pk_bf16_f32 v105, v118, v119
	v_cvt_pk_bf16_f32 v106, v120, v121
	v_cvt_pk_bf16_f32 v107, v122, v123
	v_cvt_pk_bf16_f32 v108, v124, v125
	v_cvt_pk_bf16_f32 v109, v126, v127
	v_cvt_pk_bf16_f32 v110, v128, v129
	v_cvt_pk_bf16_f32 v111, v130, v131
	global_store_dwordx2 v2, v[104:105], s[16:17] offset:0
	global_store_dwordx2 v2, v[106:107], s[16:17] offset:512
	global_store_dwordx2 v2, v[108:109], s[16:17] offset:1024
	global_store_dwordx2 v2, v[110:111], s[16:17] offset:1536
	global_store_dwordx2 v2, v[112:113], s[18:19]
	s_cmp_lt_u32 s15, 0x8400
	s_cselect_b32 s12, s15, s0
	s_cmp_lt_u32 s12, 0x8000
	s_cselect_b32 s8, s36, s38
	s_cselect_b32 s9, s37, s39
	s_cselect_b32 s10, s40, s42
	s_cselect_b32 s11, s41, s43
	s_cselect_b32 s13, 0, 0x8000
	s_sub_u32 s12, s12, s13
	s_lshl_b32 s13, s12, 12
	s_add_u32 s8, s8, s13
	s_addc_u32 s9, s9, 0
	s_lshl_b32 s13, s12, 10
	s_add_u32 s10, s10, s13
	s_addc_u32 s11, s11, 0
	global_load_dwordx4 v[84:87], v1, s[8:9] offset:0
	global_load_dwordx4 v[88:91], v1, s[8:9] offset:1024
	global_load_dwordx4 v[92:95], v1, s[8:9] offset:2048
	global_load_dwordx4 v[96:99], v1, s[8:9] offset:3072
	global_load_dwordx4 v[100:103], v22, s[10:11]
	s_add_i32 s15, s15, s1
	s_add_i32 s14, s14, s1
	s_mov_b32 s0, s14
	s_branch .Lxn_loop

.LBB0_205:
	s_andn2_b64 vcc, exec, s[64:65]
	s_cbranch_vccnz .Lzx207
	s_add_u32 s6, s10, 0x80
	s_addc_u32 s7, s11, 0
	s_add_u32 s10, s8, 0x100
	s_addc_u32 s11, s9, 0
	s_mov_b32 s8, 0
	ds_read_b128 v[152:155], v168
	ds_read_b128 v[156:159], v168 offset:1024
	ds_read_b128 v[172:175], v168 offset:2048
	ds_read_b128 v[176:179], v168 offset:3072
	ds_read_b128 v[180:183], v169
	ds_read_b128 v[186:189], v169 offset:1024
	ds_read_b128 v[190:193], v169 offset:2048
	ds_read_b128 v[194:197], v169 offset:3072
	s_add_i32 s12, s8, 2
	s_add_u32 s13, s6, 0x80
	s_addc_u32 s9, s7, 0
	s_cmp_eq_u32 s52, s8
	s_cselect_b32 s8, s86, s13
	s_cselect_b32 s9, s87, s9
	s_cselect_b32 s17, s89, s11
	s_cselect_b32 s16, s88, s10
	v_lshl_add_u64 v[160:161], s[6:7], 0, v[144:145]
	s_add_i32 m0, s90, 0xc000
	ds_read_b128 v[198:201], v170
	ds_read_b128 v[202:205], v170 offset:1024
	ds_read_b128 v[206:209], v170 offset:2048
	ds_read_b128 v[210:213], v170 offset:3072
	ds_read_b128 v[214:217], v170 offset:4096
	ds_read_b128 v[224:227], v170 offset:5120
	ds_read_b128 v[228:231], v170 offset:6144
	ds_read_b128 v[232:235], v170 offset:7168
	global_load_lds_dwordx4 v[160:161], off
	v_lshl_add_u64 v[160:161], s[6:7], 0, v[146:147]
	s_add_i32 m0, s90, 0xe000
	s_nop 0
	global_load_lds_dwordx4 v[160:161], off
	s_waitcnt vmcnt(8)
	s_waitcnt lgkmcnt(0)
	s_barrier
	s_setprio 1
	s_waitcnt lgkmcnt(0)
	v_mfma_f32_16x16x32_bf16 v[124:127], v[152:155], v[198:201], 0
	v_mfma_f32_16x16x32_bf16 v[120:123], v[172:175], v[198:201], 0
	v_mfma_f32_16x16x32_bf16 v[108:111], v[152:155], v[206:209], 0
	v_mfma_f32_16x16x32_bf16 v[104:107], v[172:175], v[206:209], 0
	v_mfma_f32_16x16x32_bf16 v[92:95], v[152:155], v[214:217], 0
	v_mfma_f32_16x16x32_bf16 v[88:91], v[172:175], v[214:217], 0
	v_mfma_f32_16x16x32_bf16 v[76:79], v[152:155], v[228:231], 0
	v_mfma_f32_16x16x32_bf16 v[72:75], v[172:175], v[228:231], 0
	v_mfma_f32_16x16x32_bf16 v[124:127], v[156:159], v[202:205], v[124:127]
	v_mfma_f32_16x16x32_bf16 v[120:123], v[176:179], v[202:205], v[120:123]
	v_mfma_f32_16x16x32_bf16 v[108:111], v[156:159], v[210:213], v[108:111]
	v_mfma_f32_16x16x32_bf16 v[104:107], v[176:179], v[210:213], v[104:107]
	v_mfma_f32_16x16x32_bf16 v[92:95], v[156:159], v[224:227], v[92:95]
	v_mfma_f32_16x16x32_bf16 v[88:91], v[176:179], v[224:227], v[88:91]
	v_mfma_f32_16x16x32_bf16 v[76:79], v[156:159], v[232:235], v[76:79]
	v_mfma_f32_16x16x32_bf16 v[72:75], v[176:179], v[232:235], v[72:75]
	s_setprio 0
	s_setprio 1
	v_mfma_f32_16x16x32_bf16 v[116:119], v[180:183], v[198:201], 0
	v_mfma_f32_16x16x32_bf16 v[112:115], v[190:193], v[198:201], 0
	v_mfma_f32_16x16x32_bf16 v[100:103], v[180:183], v[206:209], 0
	v_mfma_f32_16x16x32_bf16 v[96:99], v[190:193], v[206:209], 0
	v_mfma_f32_16x16x32_bf16 v[84:87], v[180:183], v[214:217], 0
	v_mfma_f32_16x16x32_bf16 v[80:83], v[190:193], v[214:217], 0
	v_mfma_f32_16x16x32_bf16 v[68:71], v[180:183], v[228:231], 0
	v_mfma_f32_16x16x32_bf16 v[64:67], v[190:193], v[228:231], 0
	v_mfma_f32_16x16x32_bf16 v[116:119], v[186:189], v[202:205], v[116:119]
	v_mfma_f32_16x16x32_bf16 v[112:115], v[194:197], v[202:205], v[112:115]
	v_mfma_f32_16x16x32_bf16 v[100:103], v[186:189], v[210:213], v[100:103]
	v_mfma_f32_16x16x32_bf16 v[96:99], v[194:197], v[210:213], v[96:99]
	v_mfma_f32_16x16x32_bf16 v[84:87], v[186:189], v[224:227], v[84:87]
	v_mfma_f32_16x16x32_bf16 v[80:83], v[194:197], v[224:227], v[80:83]
	v_mfma_f32_16x16x32_bf16 v[68:71], v[186:189], v[232:235], v[68:71]
	v_mfma_f32_16x16x32_bf16 v[64:67], v[194:197], v[232:235], v[64:67]
	s_setprio 0
	s_barrier
	s_add_i32 s13, s37, s31
	v_lshl_add_u64 v[160:161], s[16:17], 0, v[130:131]
	s_mov_b32 m0, s13
	ds_read_b128 v[198:201], v170 offset:16384
	ds_read_b128 v[202:205], v170 offset:17408
	ds_read_b128 v[206:209], v170 offset:18432
	ds_read_b128 v[210:213], v170 offset:19456
	ds_read_b128 v[214:217], v170 offset:20480
	ds_read_b128 v[224:227], v170 offset:21504
	ds_read_b128 v[228:231], v170 offset:22528
	ds_read_b128 v[232:235], v170 offset:23552
	global_load_lds_dwordx4 v[160:161], off
	s_add_i32 m0, s13, 0x2000
	v_lshl_add_u64 v[236:237], s[16:17], 0, v[134:135]
	s_add_u32 s16, s16, s74
	s_addc_u32 s17, s17, s75
	s_add_i32 s13, s38, s31
	global_load_lds_dwordx4 v[236:237], off
	v_lshl_add_u64 v[238:239], s[16:17], 0, v[130:131]
	s_mov_b32 m0, s13
	v_lshl_add_u64 v[240:241], s[16:17], 0, v[134:135]
	global_load_lds_dwordx4 v[238:239], off
	s_add_i32 m0, s13, 0x2000
	v_lshl_add_u64 v[242:243], s[8:9], 0, v[128:129]
	global_load_lds_dwordx4 v[240:241], off
	v_lshl_add_u64 v[244:245], s[8:9], 0, v[132:133]
	s_waitcnt vmcnt(6)
	s_waitcnt lgkmcnt(0)
	s_barrier
	s_setprio 1
	s_waitcnt lgkmcnt(0)
	v_mfma_f32_16x16x32_bf16 v[60:63], v[152:155], v[198:201], 0
	v_mfma_f32_16x16x32_bf16 v[56:59], v[172:175], v[198:201], 0
	v_mfma_f32_16x16x32_bf16 v[44:47], v[152:155], v[206:209], 0
	v_mfma_f32_16x16x32_bf16 v[40:43], v[172:175], v[206:209], 0
	v_mfma_f32_16x16x32_bf16 v[28:31], v[152:155], v[214:217], 0
	v_mfma_f32_16x16x32_bf16 v[24:27], v[172:175], v[214:217], 0
	v_mfma_f32_16x16x32_bf16 v[12:15], v[152:155], v[228:231], 0
	v_mfma_f32_16x16x32_bf16 v[8:11], v[172:175], v[228:231], 0
	v_mfma_f32_16x16x32_bf16 v[60:63], v[156:159], v[202:205], v[60:63]
	v_mfma_f32_16x16x32_bf16 v[56:59], v[176:179], v[202:205], v[56:59]
	v_mfma_f32_16x16x32_bf16 v[44:47], v[156:159], v[210:213], v[44:47]
	v_mfma_f32_16x16x32_bf16 v[40:43], v[176:179], v[210:213], v[40:43]
	v_mfma_f32_16x16x32_bf16 v[28:31], v[156:159], v[224:227], v[28:31]
	v_mfma_f32_16x16x32_bf16 v[24:27], v[176:179], v[224:227], v[24:27]
	v_mfma_f32_16x16x32_bf16 v[12:15], v[156:159], v[232:235], v[12:15]
	v_mfma_f32_16x16x32_bf16 v[8:11], v[176:179], v[232:235], v[8:11]
	s_setprio 0
	s_setprio 1
	v_mfma_f32_16x16x32_bf16 v[52:55], v[180:183], v[198:201], 0
	v_mfma_f32_16x16x32_bf16 v[48:51], v[190:193], v[198:201], 0
	v_mfma_f32_16x16x32_bf16 v[36:39], v[180:183], v[206:209], 0
	v_mfma_f32_16x16x32_bf16 v[32:35], v[190:193], v[206:209], 0
	v_mfma_f32_16x16x32_bf16 v[20:23], v[180:183], v[214:217], 0
	v_mfma_f32_16x16x32_bf16 v[16:19], v[190:193], v[214:217], 0
	v_mfma_f32_16x16x32_bf16 v[4:7], v[180:183], v[228:231], 0
	v_mfma_f32_16x16x32_bf16 v[0:3], v[190:193], v[228:231], 0
	v_mfma_f32_16x16x32_bf16 v[52:55], v[186:189], v[202:205], v[52:55]
	v_mfma_f32_16x16x32_bf16 v[48:51], v[194:197], v[202:205], v[48:51]
	v_mfma_f32_16x16x32_bf16 v[36:39], v[186:189], v[210:213], v[36:39]
	v_mfma_f32_16x16x32_bf16 v[32:35], v[194:197], v[210:213], v[32:35]
	v_mfma_f32_16x16x32_bf16 v[20:23], v[186:189], v[224:227], v[20:23]
	v_mfma_f32_16x16x32_bf16 v[16:19], v[194:197], v[224:227], v[16:19]
	v_mfma_f32_16x16x32_bf16 v[4:7], v[186:189], v[232:235], v[4:7]
	v_mfma_f32_16x16x32_bf16 v[0:3], v[194:197], v[232:235], v[0:3]
	s_setprio 0
	s_barrier
	s_add_i32 s13, 0, 0x18000
	v_add_u32_e32 v136, s13, v143
	s_add_i32 s16, 0, 0x1c000
	ds_read_b128 v[152:155], v136
	ds_read_b128 v[156:159], v136 offset:1024
	ds_read_b128 v[172:175], v136 offset:2048
	ds_read_b128 v[176:179], v136 offset:3072
	v_add_u32_e32 v136, s16, v143
	ds_read_b128 v[180:183], v136
	ds_read_b128 v[186:189], v136 offset:1024
	ds_read_b128 v[190:193], v136 offset:2048
	ds_read_b128 v[194:197], v136 offset:3072
	s_add_u32 s8, s8, s74
	s_addc_u32 s9, s9, s75
	s_mov_b32 m0, s90
	s_nop 0
	global_load_lds_dwordx4 v[242:243], off
	s_mov_b32 m0, s91
	s_nop 0
	global_load_lds_dwordx4 v[244:245], off
	s_mov_b32 m0, s78
	v_lshl_add_u64 v[246:247], s[8:9], 0, v[128:129]
	ds_read_b128 v[198:201], v170 offset:32768
	ds_read_b128 v[202:205], v170 offset:33792
	ds_read_b128 v[206:209], v170 offset:34816
	ds_read_b128 v[210:213], v170 offset:35840
	ds_read_b128 v[214:217], v170 offset:36864
	ds_read_b128 v[224:227], v170 offset:37888
	ds_read_b128 v[228:231], v170 offset:38912
	ds_read_b128 v[232:235], v170 offset:39936
	global_load_lds_dwordx4 v[246:247], off
	v_lshl_add_u64 v[246:247], s[8:9], 0, v[132:133]
	s_mov_b32 m0, s79
	s_nop 0
	global_load_lds_dwordx4 v[246:247], off
	s_waitcnt vmcnt(8)
	s_waitcnt lgkmcnt(0)
	s_barrier
	s_setprio 1
	s_waitcnt lgkmcnt(0)
	v_mfma_f32_16x16x32_bf16 v[124:127], v[152:155], v[198:201], v[124:127]
	v_mfma_f32_16x16x32_bf16 v[120:123], v[172:175], v[198:201], v[120:123]
	v_mfma_f32_16x16x32_bf16 v[108:111], v[152:155], v[206:209], v[108:111]
	v_mfma_f32_16x16x32_bf16 v[104:107], v[172:175], v[206:209], v[104:107]
	v_mfma_f32_16x16x32_bf16 v[92:95], v[152:155], v[214:217], v[92:95]
	v_mfma_f32_16x16x32_bf16 v[88:91], v[172:175], v[214:217], v[88:91]
	v_mfma_f32_16x16x32_bf16 v[76:79], v[152:155], v[228:231], v[76:79]
	v_mfma_f32_16x16x32_bf16 v[72:75], v[172:175], v[228:231], v[72:75]
	v_mfma_f32_16x16x32_bf16 v[124:127], v[156:159], v[202:205], v[124:127]
	v_mfma_f32_16x16x32_bf16 v[120:123], v[176:179], v[202:205], v[120:123]
	v_mfma_f32_16x16x32_bf16 v[108:111], v[156:159], v[210:213], v[108:111]
	v_mfma_f32_16x16x32_bf16 v[104:107], v[176:179], v[210:213], v[104:107]
	v_mfma_f32_16x16x32_bf16 v[92:95], v[156:159], v[224:227], v[92:95]
	v_mfma_f32_16x16x32_bf16 v[88:91], v[176:179], v[224:227], v[88:91]
	v_mfma_f32_16x16x32_bf16 v[76:79], v[156:159], v[232:235], v[76:79]
	v_mfma_f32_16x16x32_bf16 v[72:75], v[176:179], v[232:235], v[72:75]
	s_setprio 0
	s_setprio 1
	v_mfma_f32_16x16x32_bf16 v[116:119], v[180:183], v[198:201], v[116:119]
	v_mfma_f32_16x16x32_bf16 v[112:115], v[190:193], v[198:201], v[112:115]
	v_mfma_f32_16x16x32_bf16 v[100:103], v[180:183], v[206:209], v[100:103]
	v_mfma_f32_16x16x32_bf16 v[96:99], v[190:193], v[206:209], v[96:99]
	v_mfma_f32_16x16x32_bf16 v[84:87], v[180:183], v[214:217], v[84:87]
	v_mfma_f32_16x16x32_bf16 v[80:83], v[190:193], v[214:217], v[80:83]
	v_mfma_f32_16x16x32_bf16 v[68:71], v[180:183], v[228:231], v[68:71]
	v_mfma_f32_16x16x32_bf16 v[64:67], v[190:193], v[228:231], v[64:67]
	v_mfma_f32_16x16x32_bf16 v[116:119], v[186:189], v[202:205], v[116:119]
	v_mfma_f32_16x16x32_bf16 v[112:115], v[194:197], v[202:205], v[112:115]
	v_mfma_f32_16x16x32_bf16 v[100:103], v[186:189], v[210:213], v[100:103]
	v_mfma_f32_16x16x32_bf16 v[96:99], v[194:197], v[210:213], v[96:99]
	v_mfma_f32_16x16x32_bf16 v[84:87], v[186:189], v[224:227], v[84:87]
	v_mfma_f32_16x16x32_bf16 v[80:83], v[194:197], v[224:227], v[80:83]
	v_mfma_f32_16x16x32_bf16 v[68:71], v[186:189], v[232:235], v[68:71]
	v_mfma_f32_16x16x32_bf16 v[64:67], v[194:197], v[232:235], v[64:67]
	s_setprio 0
	s_barrier
	s_add_i32 s8, s13, s31
	v_lshl_add_u64 v[160:161], v[160:161], 0, s[92:93]
	s_mov_b32 m0, s8
	ds_read_b128 v[198:201], v170 offset:49152
	ds_read_b128 v[202:205], v170 offset:50176
	ds_read_b128 v[206:209], v170 offset:51200
	ds_read_b128 v[210:213], v170 offset:52224
	ds_read_b128 v[214:217], v170 offset:53248
	ds_read_b128 v[224:227], v170 offset:54272
	ds_read_b128 v[228:231], v170 offset:55296
	ds_read_b128 v[232:235], v170 offset:56320
	global_load_lds_dwordx4 v[160:161], off
	v_lshl_add_u64 v[160:161], v[236:237], 0, s[92:93]
	s_add_i32 m0, s8, 0x2000
	s_add_i32 s8, s16, s31
	global_load_lds_dwordx4 v[160:161], off
	v_lshl_add_u64 v[160:161], v[238:239], 0, s[92:93]
	s_mov_b32 m0, s8
	s_nop 0
	global_load_lds_dwordx4 v[160:161], off
	v_lshl_add_u64 v[160:161], v[240:241], 0, s[92:93]
	s_add_i32 m0, s8, 0x2000
	s_nop 0
	global_load_lds_dwordx4 v[160:161], off
	s_waitcnt vmcnt(6)
	s_waitcnt lgkmcnt(0)
	s_barrier
	s_setprio 1
	s_waitcnt lgkmcnt(0)
	v_mfma_f32_16x16x32_bf16 v[60:63], v[152:155], v[198:201], v[60:63]
	v_mfma_f32_16x16x32_bf16 v[56:59], v[172:175], v[198:201], v[56:59]
	v_mfma_f32_16x16x32_bf16 v[44:47], v[152:155], v[206:209], v[44:47]
	v_mfma_f32_16x16x32_bf16 v[40:43], v[172:175], v[206:209], v[40:43]
	v_mfma_f32_16x16x32_bf16 v[28:31], v[152:155], v[214:217], v[28:31]
	v_mfma_f32_16x16x32_bf16 v[24:27], v[172:175], v[214:217], v[24:27]
	v_mfma_f32_16x16x32_bf16 v[12:15], v[152:155], v[228:231], v[12:15]
	v_mfma_f32_16x16x32_bf16 v[8:11], v[172:175], v[228:231], v[8:11]
	v_mfma_f32_16x16x32_bf16 v[60:63], v[156:159], v[202:205], v[60:63]
	v_mfma_f32_16x16x32_bf16 v[56:59], v[176:179], v[202:205], v[56:59]
	v_mfma_f32_16x16x32_bf16 v[44:47], v[156:159], v[210:213], v[44:47]
	v_mfma_f32_16x16x32_bf16 v[40:43], v[176:179], v[210:213], v[40:43]
	v_mfma_f32_16x16x32_bf16 v[28:31], v[156:159], v[224:227], v[28:31]
	v_mfma_f32_16x16x32_bf16 v[24:27], v[176:179], v[224:227], v[24:27]
	v_mfma_f32_16x16x32_bf16 v[12:15], v[156:159], v[232:235], v[12:15]
	v_mfma_f32_16x16x32_bf16 v[8:11], v[176:179], v[232:235], v[8:11]
	s_setprio 0
	s_setprio 1
	v_mfma_f32_16x16x32_bf16 v[52:55], v[180:183], v[198:201], v[52:55]
	v_mfma_f32_16x16x32_bf16 v[48:51], v[190:193], v[198:201], v[48:51]
	v_mfma_f32_16x16x32_bf16 v[36:39], v[180:183], v[206:209], v[36:39]
	v_mfma_f32_16x16x32_bf16 v[32:35], v[190:193], v[206:209], v[32:35]
	v_mfma_f32_16x16x32_bf16 v[20:23], v[180:183], v[214:217], v[20:23]
	v_mfma_f32_16x16x32_bf16 v[16:19], v[190:193], v[214:217], v[16:19]
	v_mfma_f32_16x16x32_bf16 v[4:7], v[180:183], v[228:231], v[4:7]
	v_mfma_f32_16x16x32_bf16 v[0:3], v[190:193], v[228:231], v[0:3]
	v_mfma_f32_16x16x32_bf16 v[52:55], v[186:189], v[202:205], v[52:55]
	v_mfma_f32_16x16x32_bf16 v[48:51], v[194:197], v[202:205], v[48:51]
	v_mfma_f32_16x16x32_bf16 v[36:39], v[186:189], v[210:213], v[36:39]
	v_mfma_f32_16x16x32_bf16 v[32:35], v[194:197], v[210:213], v[32:35]
	v_mfma_f32_16x16x32_bf16 v[20:23], v[186:189], v[224:227], v[20:23]
	v_mfma_f32_16x16x32_bf16 v[16:19], v[194:197], v[224:227], v[16:19]
	v_mfma_f32_16x16x32_bf16 v[4:7], v[186:189], v[232:235], v[4:7]
	v_mfma_f32_16x16x32_bf16 v[0:3], v[194:197], v[232:235], v[0:3]
	s_setprio 0
	s_barrier
	s_add_u32 s6, s6, 0x100
	s_addc_u32 s7, s7, 0
	s_add_u32 s10, s10, 0x100
	s_addc_u32 s11, s11, 0
	s_cmp_ge_i32 s12, s36
	s_mov_b32 s8, s12
	s_cbranch_scc1 .LBB0_208

.LBB0_208:
	v_lshl_add_u64 v[160:161], v[242:243], 0, s[92:93]
	s_mov_b32 m0, s33
	s_nop 0
	global_load_lds_dwordx4 v[160:161], off
	v_lshl_add_u64 v[160:161], v[244:245], 0, s[92:93]
	s_mov_b32 m0, s28
	s_nop 0
	global_load_lds_dwordx4 v[160:161], off
	v_readlane_b32 s6, v248, 28
	v_readlane_b32 s7, v248, 29
	s_and_b64 vcc, exec, s[6:7]
	s_cbranch_vccz .LBB0_210
	s_barrier

.LBB0_640:
	s_and_b64 vcc, exec, s[4:5]
	s_waitcnt lgkmcnt(0)
	s_cbranch_vccnz .Lzx642
	s_add_u32 s56, s56, 0x80
	s_addc_u32 s57, s57, 0
	s_add_u32 s62, s58, 0x100
	s_addc_u32 s63, s59, 0
	s_mov_b32 s58, 0
	ds_read_b128 v[146:149], v153
	ds_read_b128 v[156:159], v153 offset:1024
	ds_read_b128 v[160:163], v153 offset:2048
	ds_read_b128 v[164:167], v153 offset:3072
	ds_read_b128 v[168:171], v154
	ds_read_b128 v[172:175], v154 offset:1024
	ds_read_b128 v[176:179], v154 offset:2048
	ds_read_b128 v[180:183], v154 offset:3072
	s_add_i32 s64, s58, 2
	s_add_u32 s65, s56, 0x80
	s_addc_u32 s59, s57, 0
	s_cmp_eq_u32 s49, s58
	s_cselect_b32 s58, s8, s65
	s_cselect_b32 s59, s9, s59
	s_cselect_b32 s67, s43, s63
	s_cselect_b32 s66, s42, s62
	v_lshl_add_u64 v[224:225], s[56:57], 0, v[138:139]
	s_add_i32 m0, s3, 0xc000
	ds_read_b128 v[186:189], v155
	ds_read_b128 v[190:193], v155 offset:1024
	ds_read_b128 v[194:197], v155 offset:2048
	ds_read_b128 v[198:201], v155 offset:3072
	ds_read_b128 v[202:205], v155 offset:4096
	ds_read_b128 v[206:209], v155 offset:5120
	ds_read_b128 v[210:213], v155 offset:6144
	ds_read_b128 v[214:217], v155 offset:7168
	global_load_lds_dwordx4 v[224:225], off
	v_lshl_add_u64 v[224:225], s[56:57], 0, v[140:141]
	s_add_i32 m0, s3, 0xe000
	s_nop 0
	global_load_lds_dwordx4 v[224:225], off
	s_waitcnt vmcnt(8)
	s_waitcnt lgkmcnt(0)
	s_barrier
	s_setprio 1
	s_waitcnt lgkmcnt(0)
	v_mfma_f32_16x16x32_bf16 v[124:127], v[146:149], v[186:189], 0
	v_mfma_f32_16x16x32_bf16 v[120:123], v[160:163], v[186:189], 0
	v_mfma_f32_16x16x32_bf16 v[108:111], v[146:149], v[194:197], 0
	v_mfma_f32_16x16x32_bf16 v[104:107], v[160:163], v[194:197], 0
	v_mfma_f32_16x16x32_bf16 v[92:95], v[146:149], v[202:205], 0
	v_mfma_f32_16x16x32_bf16 v[88:91], v[160:163], v[202:205], 0
	v_mfma_f32_16x16x32_bf16 v[76:79], v[146:149], v[210:213], 0
	v_mfma_f32_16x16x32_bf16 v[72:75], v[160:163], v[210:213], 0
	v_mfma_f32_16x16x32_bf16 v[124:127], v[156:159], v[190:193], v[124:127]
	v_mfma_f32_16x16x32_bf16 v[120:123], v[164:167], v[190:193], v[120:123]
	v_mfma_f32_16x16x32_bf16 v[108:111], v[156:159], v[198:201], v[108:111]
	v_mfma_f32_16x16x32_bf16 v[104:107], v[164:167], v[198:201], v[104:107]
	v_mfma_f32_16x16x32_bf16 v[92:95], v[156:159], v[206:209], v[92:95]
	v_mfma_f32_16x16x32_bf16 v[88:91], v[164:167], v[206:209], v[88:91]
	v_mfma_f32_16x16x32_bf16 v[76:79], v[156:159], v[214:217], v[76:79]
	v_mfma_f32_16x16x32_bf16 v[72:75], v[164:167], v[214:217], v[72:75]
	s_setprio 0
	s_setprio 1
	v_mfma_f32_16x16x32_bf16 v[116:119], v[168:171], v[186:189], 0
	v_mfma_f32_16x16x32_bf16 v[112:115], v[176:179], v[186:189], 0
	v_mfma_f32_16x16x32_bf16 v[100:103], v[168:171], v[194:197], 0
	v_mfma_f32_16x16x32_bf16 v[96:99], v[176:179], v[194:197], 0
	v_mfma_f32_16x16x32_bf16 v[84:87], v[168:171], v[202:205], 0
	v_mfma_f32_16x16x32_bf16 v[80:83], v[176:179], v[202:205], 0
	v_mfma_f32_16x16x32_bf16 v[68:71], v[168:171], v[210:213], 0
	v_mfma_f32_16x16x32_bf16 v[64:67], v[176:179], v[210:213], 0
	v_mfma_f32_16x16x32_bf16 v[116:119], v[172:175], v[190:193], v[116:119]
	v_mfma_f32_16x16x32_bf16 v[112:115], v[180:183], v[190:193], v[112:115]
	v_mfma_f32_16x16x32_bf16 v[100:103], v[172:175], v[198:201], v[100:103]
	v_mfma_f32_16x16x32_bf16 v[96:99], v[180:183], v[198:201], v[96:99]
	v_mfma_f32_16x16x32_bf16 v[84:87], v[172:175], v[206:209], v[84:87]
	v_mfma_f32_16x16x32_bf16 v[80:83], v[180:183], v[206:209], v[80:83]
	v_mfma_f32_16x16x32_bf16 v[68:71], v[172:175], v[214:217], v[68:71]
	v_mfma_f32_16x16x32_bf16 v[64:67], v[180:183], v[214:217], v[64:67]
	s_setprio 0
	s_barrier
	s_add_i32 s65, s50, s31
	v_lshl_add_u64 v[224:225], s[66:67], 0, v[130:131]
	s_mov_b32 m0, s65
	ds_read_b128 v[186:189], v155 offset:16384
	ds_read_b128 v[190:193], v155 offset:17408
	ds_read_b128 v[194:197], v155 offset:18432
	ds_read_b128 v[198:201], v155 offset:19456
	ds_read_b128 v[202:205], v155 offset:20480
	ds_read_b128 v[206:209], v155 offset:21504
	ds_read_b128 v[210:213], v155 offset:22528
	ds_read_b128 v[214:217], v155 offset:23552
	global_load_lds_dwordx4 v[224:225], off
	s_add_i32 m0, s65, 0x2000
	v_lshl_add_u64 v[226:227], s[66:67], 0, v[134:135]
	s_add_u32 s66, s66, s18
	s_addc_u32 s67, s67, s19
	s_add_i32 s65, s51, s31
	global_load_lds_dwordx4 v[226:227], off
	v_lshl_add_u64 v[228:229], s[66:67], 0, v[130:131]
	s_mov_b32 m0, s65
	v_lshl_add_u64 v[230:231], s[66:67], 0, v[134:135]
	global_load_lds_dwordx4 v[228:229], off
	s_add_i32 m0, s65, 0x2000
	v_lshl_add_u64 v[232:233], s[58:59], 0, v[128:129]
	global_load_lds_dwordx4 v[230:231], off
	v_lshl_add_u64 v[234:235], s[58:59], 0, v[132:133]
	s_waitcnt vmcnt(6)
	s_waitcnt lgkmcnt(0)
	s_barrier
	s_setprio 1
	s_waitcnt lgkmcnt(0)
	v_mfma_f32_16x16x32_bf16 v[60:63], v[146:149], v[186:189], 0
	v_mfma_f32_16x16x32_bf16 v[56:59], v[160:163], v[186:189], 0
	v_mfma_f32_16x16x32_bf16 v[44:47], v[146:149], v[194:197], 0
	v_mfma_f32_16x16x32_bf16 v[40:43], v[160:163], v[194:197], 0
	v_mfma_f32_16x16x32_bf16 v[28:31], v[146:149], v[202:205], 0
	v_mfma_f32_16x16x32_bf16 v[24:27], v[160:163], v[202:205], 0
	v_mfma_f32_16x16x32_bf16 v[12:15], v[146:149], v[210:213], 0
	v_mfma_f32_16x16x32_bf16 v[8:11], v[160:163], v[210:213], 0
	v_mfma_f32_16x16x32_bf16 v[60:63], v[156:159], v[190:193], v[60:63]
	v_mfma_f32_16x16x32_bf16 v[56:59], v[164:167], v[190:193], v[56:59]
	v_mfma_f32_16x16x32_bf16 v[44:47], v[156:159], v[198:201], v[44:47]
	v_mfma_f32_16x16x32_bf16 v[40:43], v[164:167], v[198:201], v[40:43]
	v_mfma_f32_16x16x32_bf16 v[28:31], v[156:159], v[206:209], v[28:31]
	v_mfma_f32_16x16x32_bf16 v[24:27], v[164:167], v[206:209], v[24:27]
	v_mfma_f32_16x16x32_bf16 v[12:15], v[156:159], v[214:217], v[12:15]
	v_mfma_f32_16x16x32_bf16 v[8:11], v[164:167], v[214:217], v[8:11]
	s_setprio 0
	s_setprio 1
	v_mfma_f32_16x16x32_bf16 v[52:55], v[168:171], v[186:189], 0
	v_mfma_f32_16x16x32_bf16 v[48:51], v[176:179], v[186:189], 0
	v_mfma_f32_16x16x32_bf16 v[36:39], v[168:171], v[194:197], 0
	v_mfma_f32_16x16x32_bf16 v[32:35], v[176:179], v[194:197], 0
	v_mfma_f32_16x16x32_bf16 v[20:23], v[168:171], v[202:205], 0
	v_mfma_f32_16x16x32_bf16 v[16:19], v[176:179], v[202:205], 0
	v_mfma_f32_16x16x32_bf16 v[4:7], v[168:171], v[210:213], 0
	v_mfma_f32_16x16x32_bf16 v[0:3], v[176:179], v[210:213], 0
	v_mfma_f32_16x16x32_bf16 v[52:55], v[172:175], v[190:193], v[52:55]
	v_mfma_f32_16x16x32_bf16 v[48:51], v[180:183], v[190:193], v[48:51]
	v_mfma_f32_16x16x32_bf16 v[36:39], v[172:175], v[198:201], v[36:39]
	v_mfma_f32_16x16x32_bf16 v[32:35], v[180:183], v[198:201], v[32:35]
	v_mfma_f32_16x16x32_bf16 v[20:23], v[172:175], v[206:209], v[20:23]
	v_mfma_f32_16x16x32_bf16 v[16:19], v[180:183], v[206:209], v[16:19]
	v_mfma_f32_16x16x32_bf16 v[4:7], v[172:175], v[214:217], v[4:7]
	v_mfma_f32_16x16x32_bf16 v[0:3], v[180:183], v[214:217], v[0:3]
	s_setprio 0
	s_barrier
	s_add_i32 s65, 0, 0x18000
	v_add_u32_e32 v136, s65, v151
	s_add_i32 s66, 0, 0x1c000
	ds_read_b128 v[146:149], v136
	ds_read_b128 v[156:159], v136 offset:1024
	ds_read_b128 v[160:163], v136 offset:2048
	ds_read_b128 v[164:167], v136 offset:3072
	v_add_u32_e32 v136, s66, v151
	ds_read_b128 v[168:171], v136
	ds_read_b128 v[172:175], v136 offset:1024
	ds_read_b128 v[176:179], v136 offset:2048
	ds_read_b128 v[180:183], v136 offset:3072
	s_add_u32 s58, s58, s18
	s_addc_u32 s59, s59, s19
	s_mov_b32 m0, s3
	s_nop 0
	global_load_lds_dwordx4 v[232:233], off
	s_mov_b32 m0, s28
	s_nop 0
	global_load_lds_dwordx4 v[234:235], off
	s_mov_b32 m0, s33
	v_lshl_add_u64 v[236:237], s[58:59], 0, v[128:129]
	ds_read_b128 v[186:189], v155 offset:32768
	ds_read_b128 v[190:193], v155 offset:33792
	ds_read_b128 v[194:197], v155 offset:34816
	ds_read_b128 v[198:201], v155 offset:35840
	ds_read_b128 v[202:205], v155 offset:36864
	ds_read_b128 v[206:209], v155 offset:37888
	ds_read_b128 v[210:213], v155 offset:38912
	ds_read_b128 v[214:217], v155 offset:39936
	global_load_lds_dwordx4 v[236:237], off
	v_lshl_add_u64 v[236:237], s[58:59], 0, v[132:133]
	s_mov_b32 m0, s44
	s_nop 0
	global_load_lds_dwordx4 v[236:237], off
	s_waitcnt vmcnt(8)
	s_waitcnt lgkmcnt(0)
	s_barrier
	s_setprio 1
	s_waitcnt lgkmcnt(0)
	v_mfma_f32_16x16x32_bf16 v[124:127], v[146:149], v[186:189], v[124:127]
	v_mfma_f32_16x16x32_bf16 v[120:123], v[160:163], v[186:189], v[120:123]
	v_mfma_f32_16x16x32_bf16 v[108:111], v[146:149], v[194:197], v[108:111]
	v_mfma_f32_16x16x32_bf16 v[104:107], v[160:163], v[194:197], v[104:107]
	v_mfma_f32_16x16x32_bf16 v[92:95], v[146:149], v[202:205], v[92:95]
	v_mfma_f32_16x16x32_bf16 v[88:91], v[160:163], v[202:205], v[88:91]
	v_mfma_f32_16x16x32_bf16 v[76:79], v[146:149], v[210:213], v[76:79]
	v_mfma_f32_16x16x32_bf16 v[72:75], v[160:163], v[210:213], v[72:75]
	v_mfma_f32_16x16x32_bf16 v[124:127], v[156:159], v[190:193], v[124:127]
	v_mfma_f32_16x16x32_bf16 v[120:123], v[164:167], v[190:193], v[120:123]
	v_mfma_f32_16x16x32_bf16 v[108:111], v[156:159], v[198:201], v[108:111]
	v_mfma_f32_16x16x32_bf16 v[104:107], v[164:167], v[198:201], v[104:107]
	v_mfma_f32_16x16x32_bf16 v[92:95], v[156:159], v[206:209], v[92:95]
	v_mfma_f32_16x16x32_bf16 v[88:91], v[164:167], v[206:209], v[88:91]
	v_mfma_f32_16x16x32_bf16 v[76:79], v[156:159], v[214:217], v[76:79]
	v_mfma_f32_16x16x32_bf16 v[72:75], v[164:167], v[214:217], v[72:75]
	s_setprio 0
	s_setprio 1
	v_mfma_f32_16x16x32_bf16 v[116:119], v[168:171], v[186:189], v[116:119]
	v_mfma_f32_16x16x32_bf16 v[112:115], v[176:179], v[186:189], v[112:115]
	v_mfma_f32_16x16x32_bf16 v[100:103], v[168:171], v[194:197], v[100:103]
	v_mfma_f32_16x16x32_bf16 v[96:99], v[176:179], v[194:197], v[96:99]
	v_mfma_f32_16x16x32_bf16 v[84:87], v[168:171], v[202:205], v[84:87]
	v_mfma_f32_16x16x32_bf16 v[80:83], v[176:179], v[202:205], v[80:83]
	v_mfma_f32_16x16x32_bf16 v[68:71], v[168:171], v[210:213], v[68:71]
	v_mfma_f32_16x16x32_bf16 v[64:67], v[176:179], v[210:213], v[64:67]
	v_mfma_f32_16x16x32_bf16 v[116:119], v[172:175], v[190:193], v[116:119]
	v_mfma_f32_16x16x32_bf16 v[112:115], v[180:183], v[190:193], v[112:115]
	v_mfma_f32_16x16x32_bf16 v[100:103], v[172:175], v[198:201], v[100:103]
	v_mfma_f32_16x16x32_bf16 v[96:99], v[180:183], v[198:201], v[96:99]
	v_mfma_f32_16x16x32_bf16 v[84:87], v[172:175], v[206:209], v[84:87]
	v_mfma_f32_16x16x32_bf16 v[80:83], v[180:183], v[206:209], v[80:83]
	v_mfma_f32_16x16x32_bf16 v[68:71], v[172:175], v[214:217], v[68:71]
	v_mfma_f32_16x16x32_bf16 v[64:67], v[180:183], v[214:217], v[64:67]
	s_setprio 0
	s_barrier
	s_add_i32 s58, s65, s31
	v_lshl_add_u64 v[224:225], v[224:225], 0, s[40:41]
	s_mov_b32 m0, s58
	ds_read_b128 v[186:189], v155 offset:49152
	ds_read_b128 v[190:193], v155 offset:50176
	ds_read_b128 v[194:197], v155 offset:51200
	ds_read_b128 v[198:201], v155 offset:52224
	ds_read_b128 v[202:205], v155 offset:53248
	ds_read_b128 v[206:209], v155 offset:54272
	ds_read_b128 v[210:213], v155 offset:55296
	ds_read_b128 v[214:217], v155 offset:56320
	global_load_lds_dwordx4 v[224:225], off
	v_lshl_add_u64 v[224:225], v[226:227], 0, s[40:41]
	s_add_i32 m0, s58, 0x2000
	s_add_i32 s58, s66, s31
	global_load_lds_dwordx4 v[224:225], off
	v_lshl_add_u64 v[224:225], v[228:229], 0, s[40:41]
	s_mov_b32 m0, s58
	s_nop 0
	global_load_lds_dwordx4 v[224:225], off
	v_lshl_add_u64 v[224:225], v[230:231], 0, s[40:41]
	s_add_i32 m0, s58, 0x2000
	s_nop 0
	global_load_lds_dwordx4 v[224:225], off
	s_waitcnt vmcnt(6)
	s_waitcnt lgkmcnt(0)
	s_barrier
	s_setprio 1
	s_waitcnt lgkmcnt(0)
	v_mfma_f32_16x16x32_bf16 v[60:63], v[146:149], v[186:189], v[60:63]
	v_mfma_f32_16x16x32_bf16 v[56:59], v[160:163], v[186:189], v[56:59]
	v_mfma_f32_16x16x32_bf16 v[44:47], v[146:149], v[194:197], v[44:47]
	v_mfma_f32_16x16x32_bf16 v[40:43], v[160:163], v[194:197], v[40:43]
	v_mfma_f32_16x16x32_bf16 v[28:31], v[146:149], v[202:205], v[28:31]
	v_mfma_f32_16x16x32_bf16 v[24:27], v[160:163], v[202:205], v[24:27]
	v_mfma_f32_16x16x32_bf16 v[12:15], v[146:149], v[210:213], v[12:15]
	v_mfma_f32_16x16x32_bf16 v[8:11], v[160:163], v[210:213], v[8:11]
	v_mfma_f32_16x16x32_bf16 v[60:63], v[156:159], v[190:193], v[60:63]
	v_mfma_f32_16x16x32_bf16 v[56:59], v[164:167], v[190:193], v[56:59]
	v_mfma_f32_16x16x32_bf16 v[44:47], v[156:159], v[198:201], v[44:47]
	v_mfma_f32_16x16x32_bf16 v[40:43], v[164:167], v[198:201], v[40:43]
	v_mfma_f32_16x16x32_bf16 v[28:31], v[156:159], v[206:209], v[28:31]
	v_mfma_f32_16x16x32_bf16 v[24:27], v[164:167], v[206:209], v[24:27]
	v_mfma_f32_16x16x32_bf16 v[12:15], v[156:159], v[214:217], v[12:15]
	v_mfma_f32_16x16x32_bf16 v[8:11], v[164:167], v[214:217], v[8:11]
	s_setprio 0
	s_setprio 1
	v_mfma_f32_16x16x32_bf16 v[52:55], v[168:171], v[186:189], v[52:55]
	v_mfma_f32_16x16x32_bf16 v[48:51], v[176:179], v[186:189], v[48:51]
	v_mfma_f32_16x16x32_bf16 v[36:39], v[168:171], v[194:197], v[36:39]
	v_mfma_f32_16x16x32_bf16 v[32:35], v[176:179], v[194:197], v[32:35]
	v_mfma_f32_16x16x32_bf16 v[20:23], v[168:171], v[202:205], v[20:23]
	v_mfma_f32_16x16x32_bf16 v[16:19], v[176:179], v[202:205], v[16:19]
	v_mfma_f32_16x16x32_bf16 v[4:7], v[168:171], v[210:213], v[4:7]
	v_mfma_f32_16x16x32_bf16 v[0:3], v[176:179], v[210:213], v[0:3]
	v_mfma_f32_16x16x32_bf16 v[52:55], v[172:175], v[190:193], v[52:55]
	v_mfma_f32_16x16x32_bf16 v[48:51], v[180:183], v[190:193], v[48:51]
	v_mfma_f32_16x16x32_bf16 v[36:39], v[172:175], v[198:201], v[36:39]
	v_mfma_f32_16x16x32_bf16 v[32:35], v[180:183], v[198:201], v[32:35]
	v_mfma_f32_16x16x32_bf16 v[20:23], v[172:175], v[206:209], v[20:23]
	v_mfma_f32_16x16x32_bf16 v[16:19], v[180:183], v[206:209], v[16:19]
	v_mfma_f32_16x16x32_bf16 v[4:7], v[172:175], v[214:217], v[4:7]
	v_mfma_f32_16x16x32_bf16 v[0:3], v[180:183], v[214:217], v[0:3]
	s_setprio 0
	s_barrier
	s_add_u32 s56, s56, 0x100
	s_addc_u32 s57, s57, 0
	s_add_u32 s62, s62, 0x100
	s_addc_u32 s63, s63, 0
	s_cmp_ge_i32 s64, s45
	s_mov_b32 s58, s64
	s_cbranch_scc1 .LBB0_643

.LBB0_643:
	v_lshl_add_u64 v[224:225], v[232:233], 0, s[40:41]
	s_mov_b32 m0, s47
	s_nop 0
	global_load_lds_dwordx4 v[224:225], off
	v_lshl_add_u64 v[224:225], v[234:235], 0, s[40:41]
	s_mov_b32 m0, s48
	s_nop 0
	global_load_lds_dwordx4 v[224:225], off
	s_and_b64 vcc, exec, s[94:95]
	s_cbranch_vccz .LBB0_645
	s_barrier

.LBB0_677:
	s_andn2_b64 vcc, exec, s[42:43]
	s_cbranch_vccnz .Lzx679
	s_add_u32 s58, s58, 0x80
	s_addc_u32 s59, s59, 0
	s_add_u32 s71, s60, 0x100
	s_addc_u32 s78, s61, 0
	s_mov_b32 s60, 0
	ds_read_b128 v[150:153], v147
	ds_read_b128 v[154:157], v147 offset:1024
	ds_read_b128 v[158:161], v147 offset:2048
	ds_read_b128 v[162:165], v147 offset:3072
	ds_read_b128 v[166:169], v148
	ds_read_b128 v[170:173], v148 offset:1024
	ds_read_b128 v[174:177], v148 offset:2048
	ds_read_b128 v[178:181], v148 offset:3072
	s_add_i32 s79, s60, 2
	s_add_u32 s80, s58, 0x80
	s_addc_u32 s61, s59, 0
	s_cmp_eq_u32 s65, s60
	s_cselect_b32 s60, s4, s80
	s_cselect_b32 s61, s5, s61
	s_cselect_b32 s81, s57, s78
	s_cselect_b32 s80, s56, s71
	v_lshl_add_u64 v[182:183], s[58:59], 0, v[136:137]
	s_add_i32 m0, s45, 0xc000
	ds_read_b128 v[186:189], v149
	ds_read_b128 v[190:193], v149 offset:1024
	ds_read_b128 v[194:197], v149 offset:2048
	ds_read_b128 v[198:201], v149 offset:3072
	ds_read_b128 v[202:205], v149 offset:4096
	ds_read_b128 v[206:209], v149 offset:5120
	ds_read_b128 v[210:213], v149 offset:6144
	ds_read_b128 v[214:217], v149 offset:7168
	global_load_lds_dwordx4 v[182:183], off
	v_lshl_add_u64 v[182:183], s[58:59], 0, v[138:139]
	s_add_i32 m0, s45, 0xe000
	s_nop 0
	global_load_lds_dwordx4 v[182:183], off
	s_waitcnt vmcnt(8)
	s_waitcnt lgkmcnt(0)
	s_barrier
	s_setprio 1
	s_waitcnt lgkmcnt(0)
	v_mfma_f32_16x16x32_bf16 v[120:123], v[150:153], v[186:189], 0
	v_mfma_f32_16x16x32_bf16 v[124:127], v[158:161], v[186:189], 0
	v_mfma_f32_16x16x32_bf16 v[108:111], v[150:153], v[194:197], 0
	v_mfma_f32_16x16x32_bf16 v[104:107], v[158:161], v[194:197], 0
	v_mfma_f32_16x16x32_bf16 v[92:95], v[150:153], v[202:205], 0
	v_mfma_f32_16x16x32_bf16 v[88:91], v[158:161], v[202:205], 0
	v_mfma_f32_16x16x32_bf16 v[76:79], v[150:153], v[210:213], 0
	v_mfma_f32_16x16x32_bf16 v[72:75], v[158:161], v[210:213], 0
	v_mfma_f32_16x16x32_bf16 v[120:123], v[154:157], v[190:193], v[120:123]
	v_mfma_f32_16x16x32_bf16 v[124:127], v[162:165], v[190:193], v[124:127]
	v_mfma_f32_16x16x32_bf16 v[108:111], v[154:157], v[198:201], v[108:111]
	v_mfma_f32_16x16x32_bf16 v[104:107], v[162:165], v[198:201], v[104:107]
	v_mfma_f32_16x16x32_bf16 v[92:95], v[154:157], v[206:209], v[92:95]
	v_mfma_f32_16x16x32_bf16 v[88:91], v[162:165], v[206:209], v[88:91]
	v_mfma_f32_16x16x32_bf16 v[76:79], v[154:157], v[214:217], v[76:79]
	v_mfma_f32_16x16x32_bf16 v[72:75], v[162:165], v[214:217], v[72:75]
	s_setprio 0
	s_setprio 1
	v_mfma_f32_16x16x32_bf16 v[116:119], v[166:169], v[186:189], 0
	v_mfma_f32_16x16x32_bf16 v[112:115], v[174:177], v[186:189], 0
	v_mfma_f32_16x16x32_bf16 v[100:103], v[166:169], v[194:197], 0
	v_mfma_f32_16x16x32_bf16 v[96:99], v[174:177], v[194:197], 0
	v_mfma_f32_16x16x32_bf16 v[84:87], v[166:169], v[202:205], 0
	v_mfma_f32_16x16x32_bf16 v[80:83], v[174:177], v[202:205], 0
	v_mfma_f32_16x16x32_bf16 v[68:71], v[166:169], v[210:213], 0
	v_mfma_f32_16x16x32_bf16 v[64:67], v[174:177], v[210:213], 0
	v_mfma_f32_16x16x32_bf16 v[116:119], v[170:173], v[190:193], v[116:119]
	v_mfma_f32_16x16x32_bf16 v[112:115], v[178:181], v[190:193], v[112:115]
	v_mfma_f32_16x16x32_bf16 v[100:103], v[170:173], v[198:201], v[100:103]
	v_mfma_f32_16x16x32_bf16 v[96:99], v[178:181], v[198:201], v[96:99]
	v_mfma_f32_16x16x32_bf16 v[84:87], v[170:173], v[206:209], v[84:87]
	v_mfma_f32_16x16x32_bf16 v[80:83], v[178:181], v[206:209], v[80:83]
	v_mfma_f32_16x16x32_bf16 v[68:71], v[170:173], v[214:217], v[68:71]
	v_mfma_f32_16x16x32_bf16 v[64:67], v[178:181], v[214:217], v[64:67]
	s_setprio 0
	s_barrier
	s_add_i32 s82, s66, s31
	v_lshl_add_u64 v[182:183], s[80:81], 0, v[132:133]
	s_mov_b32 m0, s82
	ds_read_b128 v[186:189], v149 offset:16384
	ds_read_b128 v[190:193], v149 offset:17408
	ds_read_b128 v[194:197], v149 offset:18432
	ds_read_b128 v[198:201], v149 offset:19456
	ds_read_b128 v[202:205], v149 offset:20480
	ds_read_b128 v[206:209], v149 offset:21504
	ds_read_b128 v[210:213], v149 offset:22528
	ds_read_b128 v[214:217], v149 offset:23552
	global_load_lds_dwordx4 v[182:183], off
	s_add_i32 m0, s82, 0x2000
	v_lshl_add_u64 v[224:225], s[80:81], 0, v[128:129]
	s_add_u32 s80, s80, s36
	s_addc_u32 s81, s81, s37
	s_add_i32 s82, s67, s31
	global_load_lds_dwordx4 v[224:225], off
	v_lshl_add_u64 v[226:227], s[80:81], 0, v[132:133]
	s_mov_b32 m0, s82
	v_lshl_add_u64 v[228:229], s[80:81], 0, v[128:129]
	global_load_lds_dwordx4 v[226:227], off
	s_add_i32 m0, s82, 0x2000
	v_lshl_add_u64 v[230:231], s[60:61], 0, v[134:135]
	global_load_lds_dwordx4 v[228:229], off
	v_lshl_add_u64 v[232:233], s[60:61], 0, v[130:131]
	s_waitcnt vmcnt(6)
	s_waitcnt lgkmcnt(0)
	s_barrier
	s_setprio 1
	s_waitcnt lgkmcnt(0)
	v_mfma_f32_16x16x32_bf16 v[60:63], v[150:153], v[186:189], 0
	v_mfma_f32_16x16x32_bf16 v[56:59], v[158:161], v[186:189], 0
	v_mfma_f32_16x16x32_bf16 v[44:47], v[150:153], v[194:197], 0
	v_mfma_f32_16x16x32_bf16 v[40:43], v[158:161], v[194:197], 0
	v_mfma_f32_16x16x32_bf16 v[28:31], v[150:153], v[202:205], 0
	v_mfma_f32_16x16x32_bf16 v[24:27], v[158:161], v[202:205], 0
	v_mfma_f32_16x16x32_bf16 v[12:15], v[150:153], v[210:213], 0
	v_mfma_f32_16x16x32_bf16 v[8:11], v[158:161], v[210:213], 0
	v_mfma_f32_16x16x32_bf16 v[60:63], v[154:157], v[190:193], v[60:63]
	v_mfma_f32_16x16x32_bf16 v[56:59], v[162:165], v[190:193], v[56:59]
	v_mfma_f32_16x16x32_bf16 v[44:47], v[154:157], v[198:201], v[44:47]
	v_mfma_f32_16x16x32_bf16 v[40:43], v[162:165], v[198:201], v[40:43]
	v_mfma_f32_16x16x32_bf16 v[28:31], v[154:157], v[206:209], v[28:31]
	v_mfma_f32_16x16x32_bf16 v[24:27], v[162:165], v[206:209], v[24:27]
	v_mfma_f32_16x16x32_bf16 v[12:15], v[154:157], v[214:217], v[12:15]
	v_mfma_f32_16x16x32_bf16 v[8:11], v[162:165], v[214:217], v[8:11]
	s_setprio 0
	s_setprio 1
	v_mfma_f32_16x16x32_bf16 v[52:55], v[166:169], v[186:189], 0
	v_mfma_f32_16x16x32_bf16 v[48:51], v[174:177], v[186:189], 0
	v_mfma_f32_16x16x32_bf16 v[36:39], v[166:169], v[194:197], 0
	v_mfma_f32_16x16x32_bf16 v[32:35], v[174:177], v[194:197], 0
	v_mfma_f32_16x16x32_bf16 v[20:23], v[166:169], v[202:205], 0
	v_mfma_f32_16x16x32_bf16 v[16:19], v[174:177], v[202:205], 0
	v_mfma_f32_16x16x32_bf16 v[4:7], v[166:169], v[210:213], 0
	v_mfma_f32_16x16x32_bf16 v[0:3], v[174:177], v[210:213], 0
	v_mfma_f32_16x16x32_bf16 v[52:55], v[170:173], v[190:193], v[52:55]
	v_mfma_f32_16x16x32_bf16 v[48:51], v[178:181], v[190:193], v[48:51]
	v_mfma_f32_16x16x32_bf16 v[36:39], v[170:173], v[198:201], v[36:39]
	v_mfma_f32_16x16x32_bf16 v[32:35], v[178:181], v[198:201], v[32:35]
	v_mfma_f32_16x16x32_bf16 v[20:23], v[170:173], v[206:209], v[20:23]
	v_mfma_f32_16x16x32_bf16 v[16:19], v[178:181], v[206:209], v[16:19]
	v_mfma_f32_16x16x32_bf16 v[4:7], v[170:173], v[214:217], v[4:7]
	v_mfma_f32_16x16x32_bf16 v[0:3], v[178:181], v[214:217], v[0:3]
	s_setprio 0
	s_barrier
	s_add_i32 s80, 0, 0x18000
	s_add_i32 s81, 0, 0x1c000
	v_add_u32_e32 v162, s80, v145
	v_add_u32_e32 v178, s81, v145
	ds_read_b128 v[150:153], v162
	ds_read_b128 v[154:157], v162 offset:1024
	ds_read_b128 v[158:161], v162 offset:2048
	ds_read_b128 v[162:165], v162 offset:3072
	ds_read_b128 v[166:169], v178
	ds_read_b128 v[170:173], v178 offset:1024
	ds_read_b128 v[174:177], v178 offset:2048
	ds_read_b128 v[178:181], v178 offset:3072
	s_add_u32 s60, s60, s36
	s_addc_u32 s61, s61, s37
	s_mov_b32 m0, s45
	s_nop 0
	global_load_lds_dwordx4 v[230:231], off
	s_mov_b32 m0, s46
	s_nop 0
	global_load_lds_dwordx4 v[232:233], off
	s_mov_b32 m0, s47
	v_lshl_add_u64 v[234:235], s[60:61], 0, v[134:135]
	ds_read_b128 v[186:189], v149 offset:32768
	ds_read_b128 v[190:193], v149 offset:33792
	ds_read_b128 v[194:197], v149 offset:34816
	ds_read_b128 v[198:201], v149 offset:35840
	ds_read_b128 v[202:205], v149 offset:36864
	ds_read_b128 v[206:209], v149 offset:37888
	ds_read_b128 v[210:213], v149 offset:38912
	ds_read_b128 v[214:217], v149 offset:39936
	global_load_lds_dwordx4 v[234:235], off
	v_lshl_add_u64 v[234:235], s[60:61], 0, v[130:131]
	s_mov_b32 m0, s48
	s_nop 0
	global_load_lds_dwordx4 v[234:235], off
	s_waitcnt vmcnt(8)
	s_waitcnt lgkmcnt(0)
	s_barrier
	s_setprio 1
	s_waitcnt lgkmcnt(0)
	v_mfma_f32_16x16x32_bf16 v[120:123], v[150:153], v[186:189], v[120:123]
	v_mfma_f32_16x16x32_bf16 v[124:127], v[158:161], v[186:189], v[124:127]
	v_mfma_f32_16x16x32_bf16 v[108:111], v[150:153], v[194:197], v[108:111]
	v_mfma_f32_16x16x32_bf16 v[104:107], v[158:161], v[194:197], v[104:107]
	v_mfma_f32_16x16x32_bf16 v[92:95], v[150:153], v[202:205], v[92:95]
	v_mfma_f32_16x16x32_bf16 v[88:91], v[158:161], v[202:205], v[88:91]
	v_mfma_f32_16x16x32_bf16 v[76:79], v[150:153], v[210:213], v[76:79]
	v_mfma_f32_16x16x32_bf16 v[72:75], v[158:161], v[210:213], v[72:75]
	v_mfma_f32_16x16x32_bf16 v[120:123], v[154:157], v[190:193], v[120:123]
	v_mfma_f32_16x16x32_bf16 v[124:127], v[162:165], v[190:193], v[124:127]
	v_mfma_f32_16x16x32_bf16 v[108:111], v[154:157], v[198:201], v[108:111]
	v_mfma_f32_16x16x32_bf16 v[104:107], v[162:165], v[198:201], v[104:107]
	v_mfma_f32_16x16x32_bf16 v[92:95], v[154:157], v[206:209], v[92:95]
	v_mfma_f32_16x16x32_bf16 v[88:91], v[162:165], v[206:209], v[88:91]
	v_mfma_f32_16x16x32_bf16 v[76:79], v[154:157], v[214:217], v[76:79]
	v_mfma_f32_16x16x32_bf16 v[72:75], v[162:165], v[214:217], v[72:75]
	s_setprio 0
	s_setprio 1
	v_mfma_f32_16x16x32_bf16 v[116:119], v[166:169], v[186:189], v[116:119]
	v_mfma_f32_16x16x32_bf16 v[112:115], v[174:177], v[186:189], v[112:115]
	v_mfma_f32_16x16x32_bf16 v[100:103], v[166:169], v[194:197], v[100:103]
	v_mfma_f32_16x16x32_bf16 v[96:99], v[174:177], v[194:197], v[96:99]
	v_mfma_f32_16x16x32_bf16 v[84:87], v[166:169], v[202:205], v[84:87]
	v_mfma_f32_16x16x32_bf16 v[80:83], v[174:177], v[202:205], v[80:83]
	v_mfma_f32_16x16x32_bf16 v[68:71], v[166:169], v[210:213], v[68:71]
	v_mfma_f32_16x16x32_bf16 v[64:67], v[174:177], v[210:213], v[64:67]
	v_mfma_f32_16x16x32_bf16 v[116:119], v[170:173], v[190:193], v[116:119]
	v_mfma_f32_16x16x32_bf16 v[112:115], v[178:181], v[190:193], v[112:115]
	v_mfma_f32_16x16x32_bf16 v[100:103], v[170:173], v[198:201], v[100:103]
	v_mfma_f32_16x16x32_bf16 v[96:99], v[178:181], v[198:201], v[96:99]
	v_mfma_f32_16x16x32_bf16 v[84:87], v[170:173], v[206:209], v[84:87]
	v_mfma_f32_16x16x32_bf16 v[80:83], v[178:181], v[206:209], v[80:83]
	v_mfma_f32_16x16x32_bf16 v[68:71], v[170:173], v[214:217], v[68:71]
	v_mfma_f32_16x16x32_bf16 v[64:67], v[178:181], v[214:217], v[64:67]
	s_setprio 0
	s_barrier
	s_add_i32 s60, s80, s31
	v_lshl_add_u64 v[182:183], v[182:183], 0, s[40:41]
	s_mov_b32 m0, s60
	ds_read_b128 v[186:189], v149 offset:49152
	ds_read_b128 v[190:193], v149 offset:50176
	ds_read_b128 v[194:197], v149 offset:51200
	ds_read_b128 v[198:201], v149 offset:52224
	ds_read_b128 v[202:205], v149 offset:53248
	ds_read_b128 v[206:209], v149 offset:54272
	ds_read_b128 v[210:213], v149 offset:55296
	ds_read_b128 v[214:217], v149 offset:56320
	global_load_lds_dwordx4 v[182:183], off
	v_lshl_add_u64 v[182:183], v[224:225], 0, s[40:41]
	s_add_i32 m0, s60, 0x2000
	s_add_i32 s60, s81, s31
	global_load_lds_dwordx4 v[182:183], off
	v_lshl_add_u64 v[182:183], v[226:227], 0, s[40:41]
	s_mov_b32 m0, s60
	s_nop 0
	global_load_lds_dwordx4 v[182:183], off
	v_lshl_add_u64 v[182:183], v[228:229], 0, s[40:41]
	s_add_i32 m0, s60, 0x2000
	s_nop 0
	global_load_lds_dwordx4 v[182:183], off
	s_waitcnt vmcnt(6)
	s_waitcnt lgkmcnt(0)
	s_barrier
	s_setprio 1
	s_waitcnt lgkmcnt(0)
	v_mfma_f32_16x16x32_bf16 v[60:63], v[150:153], v[186:189], v[60:63]
	v_mfma_f32_16x16x32_bf16 v[56:59], v[158:161], v[186:189], v[56:59]
	v_mfma_f32_16x16x32_bf16 v[44:47], v[150:153], v[194:197], v[44:47]
	v_mfma_f32_16x16x32_bf16 v[40:43], v[158:161], v[194:197], v[40:43]
	v_mfma_f32_16x16x32_bf16 v[28:31], v[150:153], v[202:205], v[28:31]
	v_mfma_f32_16x16x32_bf16 v[24:27], v[158:161], v[202:205], v[24:27]
	v_mfma_f32_16x16x32_bf16 v[12:15], v[150:153], v[210:213], v[12:15]
	v_mfma_f32_16x16x32_bf16 v[8:11], v[158:161], v[210:213], v[8:11]
	v_mfma_f32_16x16x32_bf16 v[60:63], v[154:157], v[190:193], v[60:63]
	v_mfma_f32_16x16x32_bf16 v[56:59], v[162:165], v[190:193], v[56:59]
	v_mfma_f32_16x16x32_bf16 v[44:47], v[154:157], v[198:201], v[44:47]
	v_mfma_f32_16x16x32_bf16 v[40:43], v[162:165], v[198:201], v[40:43]
	v_mfma_f32_16x16x32_bf16 v[28:31], v[154:157], v[206:209], v[28:31]
	v_mfma_f32_16x16x32_bf16 v[24:27], v[162:165], v[206:209], v[24:27]
	v_mfma_f32_16x16x32_bf16 v[12:15], v[154:157], v[214:217], v[12:15]
	v_mfma_f32_16x16x32_bf16 v[8:11], v[162:165], v[214:217], v[8:11]
	s_setprio 0
	s_setprio 1
	v_mfma_f32_16x16x32_bf16 v[52:55], v[166:169], v[186:189], v[52:55]
	v_mfma_f32_16x16x32_bf16 v[48:51], v[174:177], v[186:189], v[48:51]
	v_mfma_f32_16x16x32_bf16 v[36:39], v[166:169], v[194:197], v[36:39]
	v_mfma_f32_16x16x32_bf16 v[32:35], v[174:177], v[194:197], v[32:35]
	v_mfma_f32_16x16x32_bf16 v[20:23], v[166:169], v[202:205], v[20:23]
	v_mfma_f32_16x16x32_bf16 v[16:19], v[174:177], v[202:205], v[16:19]
	v_mfma_f32_16x16x32_bf16 v[4:7], v[166:169], v[210:213], v[4:7]
	v_mfma_f32_16x16x32_bf16 v[0:3], v[174:177], v[210:213], v[0:3]
	v_mfma_f32_16x16x32_bf16 v[52:55], v[170:173], v[190:193], v[52:55]
	v_mfma_f32_16x16x32_bf16 v[48:51], v[178:181], v[190:193], v[48:51]
	v_mfma_f32_16x16x32_bf16 v[36:39], v[170:173], v[198:201], v[36:39]
	v_mfma_f32_16x16x32_bf16 v[32:35], v[178:181], v[198:201], v[32:35]
	v_mfma_f32_16x16x32_bf16 v[20:23], v[170:173], v[206:209], v[20:23]
	v_mfma_f32_16x16x32_bf16 v[16:19], v[178:181], v[206:209], v[16:19]
	v_mfma_f32_16x16x32_bf16 v[4:7], v[170:173], v[214:217], v[4:7]
	v_mfma_f32_16x16x32_bf16 v[0:3], v[178:181], v[214:217], v[0:3]
	s_setprio 0
	s_barrier
	s_add_u32 s58, s58, 0x100
	s_addc_u32 s59, s59, 0
	s_add_u32 s71, s71, 0x100
	s_addc_u32 s78, s78, 0
	s_cmp_ge_i32 s79, s49
	s_mov_b32 s60, s79
	s_cbranch_scc1 .LBB0_681

.LBB0_681:
	v_lshl_add_u64 v[182:183], v[230:231], 0, s[40:41]
	s_mov_b32 m0, s53
	s_nop 0
	global_load_lds_dwordx4 v[182:183], off
	v_lshl_add_u64 v[182:183], v[232:233], 0, s[40:41]
	s_mov_b32 m0, s64
	s_nop 0
	global_load_lds_dwordx4 v[182:183], off
	s_and_b64 vcc, exec, s[94:95]
	s_cbranch_vccz .LBB0_683
	s_barrier

.LBB0_919:
	s_and_b64 vcc, exec, s[8:9]
	s_cbranch_vccnz .Lzx921
	s_add_u32 s40, s40, 0x80
	s_addc_u32 s41, s41, 0
	s_add_u32 s61, s42, 0x100
	s_addc_u32 s62, s43, 0
	s_mov_b32 s42, 0
	ds_read_b128 v[144:147], v153
	ds_read_b128 v[158:161], v153 offset:1024
	ds_read_b128 v[162:165], v153 offset:2048
	ds_read_b128 v[166:169], v153 offset:3072
	ds_read_b128 v[170:173], v154
	ds_read_b128 v[174:177], v154 offset:1024
	ds_read_b128 v[178:181], v154 offset:2048
	ds_read_b128 v[186:189], v154 offset:3072
	s_add_i32 s63, s42, 2
	s_add_u32 s64, s40, 0x80
	s_addc_u32 s43, s41, 0
	s_cmp_eq_u32 s50, s42
	s_cselect_b32 s42, s6, s64
	s_cselect_b32 s43, s7, s43
	s_cselect_b32 s65, s39, s62
	s_cselect_b32 s64, s38, s61
	s_mov_b32 m0, s53
	v_lshl_add_u64 v[148:149], s[40:41], 0, v[136:137]
	ds_read_b128 v[190:193], v155
	ds_read_b128 v[194:197], v155 offset:1024
	ds_read_b128 v[198:201], v155 offset:2048
	ds_read_b128 v[202:205], v155 offset:3072
	ds_read_b128 v[206:209], v155 offset:4096
	ds_read_b128 v[210:213], v155 offset:5120
	ds_read_b128 v[214:217], v155 offset:6144
	ds_read_b128 v[224:227], v155 offset:7168
	global_load_lds_dwordx4 v[148:149], off
	v_lshl_add_u64 v[148:149], s[40:41], 0, v[138:139]
	s_mov_b32 m0, s54
	s_nop 0
	global_load_lds_dwordx4 v[148:149], off
	s_waitcnt vmcnt(8)
	s_waitcnt lgkmcnt(0)
	s_barrier
	s_setprio 1
	s_waitcnt lgkmcnt(0)
	v_mfma_f32_16x16x32_bf16 v[120:123], v[144:147], v[190:193], 0
	v_mfma_f32_16x16x32_bf16 v[116:119], v[162:165], v[190:193], 0
	v_mfma_f32_16x16x32_bf16 v[108:111], v[144:147], v[198:201], 0
	v_mfma_f32_16x16x32_bf16 v[100:103], v[162:165], v[198:201], 0
	v_mfma_f32_16x16x32_bf16 v[92:95], v[144:147], v[206:209], 0
	v_mfma_f32_16x16x32_bf16 v[84:87], v[162:165], v[206:209], 0
	v_mfma_f32_16x16x32_bf16 v[76:79], v[144:147], v[214:217], 0
	v_mfma_f32_16x16x32_bf16 v[68:71], v[162:165], v[214:217], 0
	v_mfma_f32_16x16x32_bf16 v[120:123], v[158:161], v[194:197], v[120:123]
	v_mfma_f32_16x16x32_bf16 v[116:119], v[166:169], v[194:197], v[116:119]
	v_mfma_f32_16x16x32_bf16 v[108:111], v[158:161], v[202:205], v[108:111]
	v_mfma_f32_16x16x32_bf16 v[100:103], v[166:169], v[202:205], v[100:103]
	v_mfma_f32_16x16x32_bf16 v[92:95], v[158:161], v[210:213], v[92:95]
	v_mfma_f32_16x16x32_bf16 v[84:87], v[166:169], v[210:213], v[84:87]
	v_mfma_f32_16x16x32_bf16 v[76:79], v[158:161], v[224:227], v[76:79]
	v_mfma_f32_16x16x32_bf16 v[68:71], v[166:169], v[224:227], v[68:71]
	s_setprio 0
	s_setprio 1
	v_mfma_f32_16x16x32_bf16 v[124:127], v[170:173], v[190:193], 0
	v_mfma_f32_16x16x32_bf16 v[112:115], v[178:181], v[190:193], 0
	v_mfma_f32_16x16x32_bf16 v[104:107], v[170:173], v[198:201], 0
	v_mfma_f32_16x16x32_bf16 v[96:99], v[178:181], v[198:201], 0
	v_mfma_f32_16x16x32_bf16 v[88:91], v[170:173], v[206:209], 0
	v_mfma_f32_16x16x32_bf16 v[80:83], v[178:181], v[206:209], 0
	v_mfma_f32_16x16x32_bf16 v[72:75], v[170:173], v[214:217], 0
	v_mfma_f32_16x16x32_bf16 v[64:67], v[178:181], v[214:217], 0
	v_mfma_f32_16x16x32_bf16 v[124:127], v[174:177], v[194:197], v[124:127]
	v_mfma_f32_16x16x32_bf16 v[112:115], v[186:189], v[194:197], v[112:115]
	v_mfma_f32_16x16x32_bf16 v[104:107], v[174:177], v[202:205], v[104:107]
	v_mfma_f32_16x16x32_bf16 v[96:99], v[186:189], v[202:205], v[96:99]
	v_mfma_f32_16x16x32_bf16 v[88:91], v[174:177], v[210:213], v[88:91]
	v_mfma_f32_16x16x32_bf16 v[80:83], v[186:189], v[210:213], v[80:83]
	v_mfma_f32_16x16x32_bf16 v[72:75], v[174:177], v[224:227], v[72:75]
	v_mfma_f32_16x16x32_bf16 v[64:67], v[186:189], v[224:227], v[64:67]
	s_setprio 0
	s_barrier
	s_mov_b32 m0, s55
	v_lshl_add_u64 v[148:149], s[64:65], 0, v[132:133]
	v_lshl_add_u64 v[182:183], s[64:65], 0, v[128:129]
	s_add_u32 s64, s64, s16
	ds_read_b128 v[190:193], v155 offset:16384
	ds_read_b128 v[194:197], v155 offset:17408
	ds_read_b128 v[198:201], v155 offset:18432
	ds_read_b128 v[202:205], v155 offset:19456
	ds_read_b128 v[206:209], v155 offset:20480
	ds_read_b128 v[210:213], v155 offset:21504
	ds_read_b128 v[214:217], v155 offset:22528
	ds_read_b128 v[224:227], v155 offset:23552
	global_load_lds_dwordx4 v[148:149], off
	s_mov_b32 m0, s56
	s_addc_u32 s65, s65, s17
	s_add_i32 s66, s51, s31
	global_load_lds_dwordx4 v[182:183], off
	v_lshl_add_u64 v[228:229], s[64:65], 0, v[132:133]
	s_mov_b32 m0, s66
	v_lshl_add_u64 v[230:231], s[64:65], 0, v[128:129]
	global_load_lds_dwordx4 v[228:229], off
	s_add_i32 m0, s66, 0x2000
	v_lshl_add_u64 v[232:233], s[42:43], 0, v[134:135]
	global_load_lds_dwordx4 v[230:231], off
	v_lshl_add_u64 v[234:235], s[42:43], 0, v[130:131]
	s_waitcnt vmcnt(6)
	s_waitcnt lgkmcnt(0)
	s_barrier
	s_setprio 1
	s_waitcnt lgkmcnt(0)
	v_mfma_f32_16x16x32_bf16 v[60:63], v[144:147], v[190:193], 0
	v_mfma_f32_16x16x32_bf16 v[52:55], v[162:165], v[190:193], 0
	v_mfma_f32_16x16x32_bf16 v[44:47], v[144:147], v[198:201], 0
	v_mfma_f32_16x16x32_bf16 v[36:39], v[162:165], v[198:201], 0
	v_mfma_f32_16x16x32_bf16 v[28:31], v[144:147], v[206:209], 0
	v_mfma_f32_16x16x32_bf16 v[20:23], v[162:165], v[206:209], 0
	v_mfma_f32_16x16x32_bf16 v[12:15], v[144:147], v[214:217], 0
	v_mfma_f32_16x16x32_bf16 v[4:7], v[162:165], v[214:217], 0
	v_mfma_f32_16x16x32_bf16 v[60:63], v[158:161], v[194:197], v[60:63]
	v_mfma_f32_16x16x32_bf16 v[52:55], v[166:169], v[194:197], v[52:55]
	v_mfma_f32_16x16x32_bf16 v[44:47], v[158:161], v[202:205], v[44:47]
	v_mfma_f32_16x16x32_bf16 v[36:39], v[166:169], v[202:205], v[36:39]
	v_mfma_f32_16x16x32_bf16 v[28:31], v[158:161], v[210:213], v[28:31]
	v_mfma_f32_16x16x32_bf16 v[20:23], v[166:169], v[210:213], v[20:23]
	v_mfma_f32_16x16x32_bf16 v[12:15], v[158:161], v[224:227], v[12:15]
	v_mfma_f32_16x16x32_bf16 v[4:7], v[166:169], v[224:227], v[4:7]
	s_setprio 0
	s_setprio 1
	v_mfma_f32_16x16x32_bf16 v[56:59], v[170:173], v[190:193], 0
	v_mfma_f32_16x16x32_bf16 v[48:51], v[178:181], v[190:193], 0
	v_mfma_f32_16x16x32_bf16 v[40:43], v[170:173], v[198:201], 0
	v_mfma_f32_16x16x32_bf16 v[32:35], v[178:181], v[198:201], 0
	v_mfma_f32_16x16x32_bf16 v[24:27], v[170:173], v[206:209], 0
	v_mfma_f32_16x16x32_bf16 v[16:19], v[178:181], v[206:209], 0
	v_mfma_f32_16x16x32_bf16 v[8:11], v[170:173], v[214:217], 0
	v_mfma_f32_16x16x32_bf16 v[0:3], v[178:181], v[214:217], 0
	v_mfma_f32_16x16x32_bf16 v[56:59], v[174:177], v[194:197], v[56:59]
	v_mfma_f32_16x16x32_bf16 v[48:51], v[186:189], v[194:197], v[48:51]
	v_mfma_f32_16x16x32_bf16 v[40:43], v[174:177], v[202:205], v[40:43]
	v_mfma_f32_16x16x32_bf16 v[32:35], v[186:189], v[202:205], v[32:35]
	v_mfma_f32_16x16x32_bf16 v[24:27], v[174:177], v[210:213], v[24:27]
	v_mfma_f32_16x16x32_bf16 v[16:19], v[186:189], v[210:213], v[16:19]
	v_mfma_f32_16x16x32_bf16 v[8:11], v[174:177], v[224:227], v[8:11]
	v_mfma_f32_16x16x32_bf16 v[0:3], v[186:189], v[224:227], v[0:3]
	s_setprio 0
	s_barrier
	s_add_i32 s64, 0, 0x18000
	v_add_u32_e32 v157, s64, v151
	s_add_i32 s65, 0, 0x1c000
	ds_read_b128 v[144:147], v157
	ds_read_b128 v[158:161], v157 offset:1024
	ds_read_b128 v[162:165], v157 offset:2048
	ds_read_b128 v[166:169], v157 offset:3072
	v_add_u32_e32 v157, s65, v151
	ds_read_b128 v[170:173], v157
	ds_read_b128 v[174:177], v157 offset:1024
	ds_read_b128 v[178:181], v157 offset:2048
	ds_read_b128 v[186:189], v157 offset:3072
	s_add_u32 s42, s42, s16
	s_addc_u32 s43, s43, s17
	s_mov_b32 m0, s28
	s_nop 0
	global_load_lds_dwordx4 v[232:233], off
	s_mov_b32 m0, s33
	s_nop 0
	global_load_lds_dwordx4 v[234:235], off
	s_mov_b32 m0, s44
	v_lshl_add_u64 v[236:237], s[42:43], 0, v[134:135]
	ds_read_b128 v[190:193], v155 offset:32768
	ds_read_b128 v[194:197], v155 offset:33792
	ds_read_b128 v[198:201], v155 offset:34816
	ds_read_b128 v[202:205], v155 offset:35840
	ds_read_b128 v[206:209], v155 offset:36864
	ds_read_b128 v[210:213], v155 offset:37888
	ds_read_b128 v[214:217], v155 offset:38912
	ds_read_b128 v[224:227], v155 offset:39936
	global_load_lds_dwordx4 v[236:237], off
	v_lshl_add_u64 v[236:237], s[42:43], 0, v[130:131]
	s_mov_b32 m0, s45
	s_nop 0
	global_load_lds_dwordx4 v[236:237], off
	s_waitcnt vmcnt(8)
	s_waitcnt lgkmcnt(0)
	s_barrier
	s_setprio 1
	s_waitcnt lgkmcnt(0)
	v_mfma_f32_16x16x32_bf16 v[120:123], v[144:147], v[190:193], v[120:123]
	v_mfma_f32_16x16x32_bf16 v[116:119], v[162:165], v[190:193], v[116:119]
	v_mfma_f32_16x16x32_bf16 v[108:111], v[144:147], v[198:201], v[108:111]
	v_mfma_f32_16x16x32_bf16 v[100:103], v[162:165], v[198:201], v[100:103]
	v_mfma_f32_16x16x32_bf16 v[92:95], v[144:147], v[206:209], v[92:95]
	v_mfma_f32_16x16x32_bf16 v[84:87], v[162:165], v[206:209], v[84:87]
	v_mfma_f32_16x16x32_bf16 v[76:79], v[144:147], v[214:217], v[76:79]
	v_mfma_f32_16x16x32_bf16 v[68:71], v[162:165], v[214:217], v[68:71]
	v_mfma_f32_16x16x32_bf16 v[120:123], v[158:161], v[194:197], v[120:123]
	v_mfma_f32_16x16x32_bf16 v[116:119], v[166:169], v[194:197], v[116:119]
	v_mfma_f32_16x16x32_bf16 v[108:111], v[158:161], v[202:205], v[108:111]
	v_mfma_f32_16x16x32_bf16 v[100:103], v[166:169], v[202:205], v[100:103]
	v_mfma_f32_16x16x32_bf16 v[92:95], v[158:161], v[210:213], v[92:95]
	v_mfma_f32_16x16x32_bf16 v[84:87], v[166:169], v[210:213], v[84:87]
	v_mfma_f32_16x16x32_bf16 v[76:79], v[158:161], v[224:227], v[76:79]
	v_mfma_f32_16x16x32_bf16 v[68:71], v[166:169], v[224:227], v[68:71]
	s_setprio 0
	s_setprio 1
	v_mfma_f32_16x16x32_bf16 v[124:127], v[170:173], v[190:193], v[124:127]
	v_mfma_f32_16x16x32_bf16 v[112:115], v[178:181], v[190:193], v[112:115]
	v_mfma_f32_16x16x32_bf16 v[104:107], v[170:173], v[198:201], v[104:107]
	v_mfma_f32_16x16x32_bf16 v[96:99], v[178:181], v[198:201], v[96:99]
	v_mfma_f32_16x16x32_bf16 v[88:91], v[170:173], v[206:209], v[88:91]
	v_mfma_f32_16x16x32_bf16 v[80:83], v[178:181], v[206:209], v[80:83]
	v_mfma_f32_16x16x32_bf16 v[72:75], v[170:173], v[214:217], v[72:75]
	v_mfma_f32_16x16x32_bf16 v[64:67], v[178:181], v[214:217], v[64:67]
	v_mfma_f32_16x16x32_bf16 v[124:127], v[174:177], v[194:197], v[124:127]
	v_mfma_f32_16x16x32_bf16 v[112:115], v[186:189], v[194:197], v[112:115]
	v_mfma_f32_16x16x32_bf16 v[104:107], v[174:177], v[202:205], v[104:107]
	v_mfma_f32_16x16x32_bf16 v[96:99], v[186:189], v[202:205], v[96:99]
	v_mfma_f32_16x16x32_bf16 v[88:91], v[174:177], v[210:213], v[88:91]
	v_mfma_f32_16x16x32_bf16 v[80:83], v[186:189], v[210:213], v[80:83]
	v_mfma_f32_16x16x32_bf16 v[72:75], v[174:177], v[224:227], v[72:75]
	v_mfma_f32_16x16x32_bf16 v[64:67], v[186:189], v[224:227], v[64:67]
	s_setprio 0
	s_barrier
	s_add_i32 s42, s64, s31
	v_lshl_add_u64 v[148:149], v[148:149], 0, s[36:37]
	s_mov_b32 m0, s42
	ds_read_b128 v[190:193], v155 offset:49152
	ds_read_b128 v[194:197], v155 offset:50176
	ds_read_b128 v[198:201], v155 offset:51200
	ds_read_b128 v[202:205], v155 offset:52224
	ds_read_b128 v[206:209], v155 offset:53248
	ds_read_b128 v[210:213], v155 offset:54272
	ds_read_b128 v[214:217], v155 offset:55296
	ds_read_b128 v[224:227], v155 offset:56320
	global_load_lds_dwordx4 v[148:149], off
	v_lshl_add_u64 v[148:149], v[182:183], 0, s[36:37]
	s_add_i32 m0, s42, 0x2000
	s_add_i32 s42, s65, s31
	global_load_lds_dwordx4 v[148:149], off
	v_lshl_add_u64 v[148:149], v[228:229], 0, s[36:37]
	s_mov_b32 m0, s42
	s_nop 0
	global_load_lds_dwordx4 v[148:149], off
	v_lshl_add_u64 v[148:149], v[230:231], 0, s[36:37]
	s_add_i32 m0, s42, 0x2000
	s_nop 0
	global_load_lds_dwordx4 v[148:149], off
	s_waitcnt vmcnt(6)
	s_waitcnt lgkmcnt(0)
	s_barrier
	s_setprio 1
	s_waitcnt lgkmcnt(0)
	v_mfma_f32_16x16x32_bf16 v[60:63], v[144:147], v[190:193], v[60:63]
	v_mfma_f32_16x16x32_bf16 v[52:55], v[162:165], v[190:193], v[52:55]
	v_mfma_f32_16x16x32_bf16 v[44:47], v[144:147], v[198:201], v[44:47]
	v_mfma_f32_16x16x32_bf16 v[36:39], v[162:165], v[198:201], v[36:39]
	v_mfma_f32_16x16x32_bf16 v[28:31], v[144:147], v[206:209], v[28:31]
	v_mfma_f32_16x16x32_bf16 v[20:23], v[162:165], v[206:209], v[20:23]
	v_mfma_f32_16x16x32_bf16 v[12:15], v[144:147], v[214:217], v[12:15]
	v_mfma_f32_16x16x32_bf16 v[4:7], v[162:165], v[214:217], v[4:7]
	v_mfma_f32_16x16x32_bf16 v[60:63], v[158:161], v[194:197], v[60:63]
	v_mfma_f32_16x16x32_bf16 v[52:55], v[166:169], v[194:197], v[52:55]
	v_mfma_f32_16x16x32_bf16 v[44:47], v[158:161], v[202:205], v[44:47]
	v_mfma_f32_16x16x32_bf16 v[36:39], v[166:169], v[202:205], v[36:39]
	v_mfma_f32_16x16x32_bf16 v[28:31], v[158:161], v[210:213], v[28:31]
	v_mfma_f32_16x16x32_bf16 v[20:23], v[166:169], v[210:213], v[20:23]
	v_mfma_f32_16x16x32_bf16 v[12:15], v[158:161], v[224:227], v[12:15]
	v_mfma_f32_16x16x32_bf16 v[4:7], v[166:169], v[224:227], v[4:7]
	s_setprio 0
	s_setprio 1
	v_mfma_f32_16x16x32_bf16 v[56:59], v[170:173], v[190:193], v[56:59]
	v_mfma_f32_16x16x32_bf16 v[48:51], v[178:181], v[190:193], v[48:51]
	v_mfma_f32_16x16x32_bf16 v[40:43], v[170:173], v[198:201], v[40:43]
	v_mfma_f32_16x16x32_bf16 v[32:35], v[178:181], v[198:201], v[32:35]
	v_mfma_f32_16x16x32_bf16 v[24:27], v[170:173], v[206:209], v[24:27]
	v_mfma_f32_16x16x32_bf16 v[16:19], v[178:181], v[206:209], v[16:19]
	v_mfma_f32_16x16x32_bf16 v[8:11], v[170:173], v[214:217], v[8:11]
	v_mfma_f32_16x16x32_bf16 v[0:3], v[178:181], v[214:217], v[0:3]
	v_mfma_f32_16x16x32_bf16 v[56:59], v[174:177], v[194:197], v[56:59]
	v_mfma_f32_16x16x32_bf16 v[48:51], v[186:189], v[194:197], v[48:51]
	v_mfma_f32_16x16x32_bf16 v[40:43], v[174:177], v[202:205], v[40:43]
	v_mfma_f32_16x16x32_bf16 v[32:35], v[186:189], v[202:205], v[32:35]
	v_mfma_f32_16x16x32_bf16 v[24:27], v[174:177], v[210:213], v[24:27]
	v_mfma_f32_16x16x32_bf16 v[16:19], v[186:189], v[210:213], v[16:19]
	v_mfma_f32_16x16x32_bf16 v[8:11], v[174:177], v[224:227], v[8:11]
	v_mfma_f32_16x16x32_bf16 v[0:3], v[186:189], v[224:227], v[0:3]
	s_setprio 0
	s_barrier
	s_add_u32 s40, s40, 0x100
	s_addc_u32 s41, s41, 0
	s_add_u32 s61, s61, 0x100
	s_addc_u32 s62, s62, 0
	s_cmp_ge_i32 s63, s49
	s_mov_b32 s42, s63
	s_cbranch_scc1 .LBB0_922

.LBB0_922:
	v_lshl_add_u64 v[148:149], v[232:233], 0, s[36:37]
	s_mov_b32 m0, s47
	s_nop 0
	global_load_lds_dwordx4 v[148:149], off
	v_lshl_add_u64 v[148:149], v[234:235], 0, s[36:37]
	s_mov_b32 m0, s48
	s_nop 0
	global_load_lds_dwordx4 v[148:149], off
	v_lshl_add_u32 v148, s59, 8, v150
	v_lshrrev_b32_e32 v144, 4, v184
	v_lshl_add_u32 v145, v144, 4, v148
	v_lshlrev_b32_e32 v146, 6, v145
	v_add_u32_e32 v147, 0x2000, v146
	global_load_dwordx4 v[186:189], v146, s[14:15] offset:0
	global_load_dwordx4 v[190:193], v146, s[14:15] offset:16
	global_load_dwordx4 v[194:197], v146, s[14:15] offset:32
	global_load_dwordx4 v[198:201], v146, s[14:15] offset:48
	global_load_dwordx4 v[202:205], v147, s[14:15] offset:0
	global_load_dwordx4 v[206:209], v147, s[14:15] offset:16
	global_load_dwordx4 v[210:213], v147, s[14:15] offset:32
	global_load_dwordx4 v[214:217], v147, s[14:15] offset:48
	s_and_b64 vcc, exec, s[94:95]
	s_cbranch_vccz .LBB0_924
	s_barrier

.LBB0_1001:
	s_and_b64 vcc, exec, s[4:5]
	s_waitcnt lgkmcnt(0)
	s_cbranch_vccnz .Lzx1003
	s_add_u32 s44, s44, 0x80
	s_addc_u32 s45, s45, 0
	s_add_u32 s59, s46, 0x100
	s_addc_u32 s60, s47, 0
	s_mov_b32 s46, 0
	ds_read_b128 v[144:147], v151
	ds_read_b128 v[154:157], v151 offset:1024
	ds_read_b128 v[158:161], v151 offset:2048
	ds_read_b128 v[162:165], v151 offset:3072
	ds_read_b128 v[166:169], v152
	ds_read_b128 v[170:173], v152 offset:1024
	ds_read_b128 v[174:177], v152 offset:2048
	ds_read_b128 v[178:181], v152 offset:3072
	s_add_i32 s61, s46, 2
	s_add_u32 s62, s44, 0x80
	s_addc_u32 s47, s45, 0
	s_cmp_eq_u32 s52, s46
	s_cselect_b32 s46, s8, s62
	s_cselect_b32 s47, s9, s47
	s_cselect_b32 s63, s43, s60
	s_cselect_b32 s62, s42, s59
	v_lshl_add_u64 v[182:183], s[44:45], 0, v[136:137]
	s_add_i32 m0, s3, 0xc000
	ds_read_b128 v[186:189], v153
	ds_read_b128 v[190:193], v153 offset:1024
	ds_read_b128 v[194:197], v153 offset:2048
	ds_read_b128 v[198:201], v153 offset:3072
	ds_read_b128 v[202:205], v153 offset:4096
	ds_read_b128 v[206:209], v153 offset:5120
	ds_read_b128 v[210:213], v153 offset:6144
	ds_read_b128 v[214:217], v153 offset:7168
	global_load_lds_dwordx4 v[182:183], off
	v_lshl_add_u64 v[182:183], s[44:45], 0, v[138:139]
	s_add_i32 m0, s3, 0xe000
	s_nop 0
	global_load_lds_dwordx4 v[182:183], off
	s_waitcnt vmcnt(8)
	s_waitcnt lgkmcnt(0)
	s_barrier
	s_setprio 1
	s_waitcnt lgkmcnt(0)
	v_mfma_f32_16x16x32_bf16 v[124:127], v[144:147], v[186:189], 0
	v_mfma_f32_16x16x32_bf16 v[120:123], v[158:161], v[186:189], 0
	v_mfma_f32_16x16x32_bf16 v[108:111], v[144:147], v[194:197], 0
	v_mfma_f32_16x16x32_bf16 v[104:107], v[158:161], v[194:197], 0
	v_mfma_f32_16x16x32_bf16 v[92:95], v[144:147], v[202:205], 0
	v_mfma_f32_16x16x32_bf16 v[88:91], v[158:161], v[202:205], 0
	v_mfma_f32_16x16x32_bf16 v[76:79], v[144:147], v[210:213], 0
	v_mfma_f32_16x16x32_bf16 v[72:75], v[158:161], v[210:213], 0
	v_mfma_f32_16x16x32_bf16 v[124:127], v[154:157], v[190:193], v[124:127]
	v_mfma_f32_16x16x32_bf16 v[120:123], v[162:165], v[190:193], v[120:123]
	v_mfma_f32_16x16x32_bf16 v[108:111], v[154:157], v[198:201], v[108:111]
	v_mfma_f32_16x16x32_bf16 v[104:107], v[162:165], v[198:201], v[104:107]
	v_mfma_f32_16x16x32_bf16 v[92:95], v[154:157], v[206:209], v[92:95]
	v_mfma_f32_16x16x32_bf16 v[88:91], v[162:165], v[206:209], v[88:91]
	v_mfma_f32_16x16x32_bf16 v[76:79], v[154:157], v[214:217], v[76:79]
	v_mfma_f32_16x16x32_bf16 v[72:75], v[162:165], v[214:217], v[72:75]
	s_setprio 0
	s_setprio 1
	v_mfma_f32_16x16x32_bf16 v[116:119], v[166:169], v[186:189], 0
	v_mfma_f32_16x16x32_bf16 v[112:115], v[174:177], v[186:189], 0
	v_mfma_f32_16x16x32_bf16 v[100:103], v[166:169], v[194:197], 0
	v_mfma_f32_16x16x32_bf16 v[96:99], v[174:177], v[194:197], 0
	v_mfma_f32_16x16x32_bf16 v[84:87], v[166:169], v[202:205], 0
	v_mfma_f32_16x16x32_bf16 v[80:83], v[174:177], v[202:205], 0
	v_mfma_f32_16x16x32_bf16 v[68:71], v[166:169], v[210:213], 0
	v_mfma_f32_16x16x32_bf16 v[64:67], v[174:177], v[210:213], 0
	v_mfma_f32_16x16x32_bf16 v[116:119], v[170:173], v[190:193], v[116:119]
	v_mfma_f32_16x16x32_bf16 v[112:115], v[178:181], v[190:193], v[112:115]
	v_mfma_f32_16x16x32_bf16 v[100:103], v[170:173], v[198:201], v[100:103]
	v_mfma_f32_16x16x32_bf16 v[96:99], v[178:181], v[198:201], v[96:99]
	v_mfma_f32_16x16x32_bf16 v[84:87], v[170:173], v[206:209], v[84:87]
	v_mfma_f32_16x16x32_bf16 v[80:83], v[178:181], v[206:209], v[80:83]
	v_mfma_f32_16x16x32_bf16 v[68:71], v[170:173], v[214:217], v[68:71]
	v_mfma_f32_16x16x32_bf16 v[64:67], v[178:181], v[214:217], v[64:67]
	s_setprio 0
	s_barrier
	s_add_i32 s64, s53, s31
	v_lshl_add_u64 v[182:183], s[62:63], 0, v[130:131]
	s_mov_b32 m0, s64
	ds_read_b128 v[186:189], v153 offset:16384
	ds_read_b128 v[190:193], v153 offset:17408
	ds_read_b128 v[194:197], v153 offset:18432
	ds_read_b128 v[198:201], v153 offset:19456
	ds_read_b128 v[202:205], v153 offset:20480
	ds_read_b128 v[206:209], v153 offset:21504
	ds_read_b128 v[210:213], v153 offset:22528
	ds_read_b128 v[214:217], v153 offset:23552
	global_load_lds_dwordx4 v[182:183], off
	s_add_i32 m0, s64, 0x2000
	v_lshl_add_u64 v[224:225], s[62:63], 0, v[134:135]
	s_add_u32 s62, s62, s16
	s_addc_u32 s63, s63, s17
	s_add_i32 s64, s54, s31
	global_load_lds_dwordx4 v[224:225], off
	v_lshl_add_u64 v[226:227], s[62:63], 0, v[130:131]
	s_mov_b32 m0, s64
	v_lshl_add_u64 v[228:229], s[62:63], 0, v[134:135]
	global_load_lds_dwordx4 v[226:227], off
	s_add_i32 m0, s64, 0x2000
	v_lshl_add_u64 v[230:231], s[46:47], 0, v[128:129]
	global_load_lds_dwordx4 v[228:229], off
	v_lshl_add_u64 v[232:233], s[46:47], 0, v[132:133]
	s_waitcnt vmcnt(6)
	s_waitcnt lgkmcnt(0)
	s_barrier
	s_setprio 1
	s_waitcnt lgkmcnt(0)
	v_mfma_f32_16x16x32_bf16 v[60:63], v[144:147], v[186:189], 0
	v_mfma_f32_16x16x32_bf16 v[56:59], v[158:161], v[186:189], 0
	v_mfma_f32_16x16x32_bf16 v[44:47], v[144:147], v[194:197], 0
	v_mfma_f32_16x16x32_bf16 v[40:43], v[158:161], v[194:197], 0
	v_mfma_f32_16x16x32_bf16 v[28:31], v[144:147], v[202:205], 0
	v_mfma_f32_16x16x32_bf16 v[24:27], v[158:161], v[202:205], 0
	v_mfma_f32_16x16x32_bf16 v[12:15], v[144:147], v[210:213], 0
	v_mfma_f32_16x16x32_bf16 v[8:11], v[158:161], v[210:213], 0
	v_mfma_f32_16x16x32_bf16 v[60:63], v[154:157], v[190:193], v[60:63]
	v_mfma_f32_16x16x32_bf16 v[56:59], v[162:165], v[190:193], v[56:59]
	v_mfma_f32_16x16x32_bf16 v[44:47], v[154:157], v[198:201], v[44:47]
	v_mfma_f32_16x16x32_bf16 v[40:43], v[162:165], v[198:201], v[40:43]
	v_mfma_f32_16x16x32_bf16 v[28:31], v[154:157], v[206:209], v[28:31]
	v_mfma_f32_16x16x32_bf16 v[24:27], v[162:165], v[206:209], v[24:27]
	v_mfma_f32_16x16x32_bf16 v[12:15], v[154:157], v[214:217], v[12:15]
	v_mfma_f32_16x16x32_bf16 v[8:11], v[162:165], v[214:217], v[8:11]
	s_setprio 0
	s_setprio 1
	v_mfma_f32_16x16x32_bf16 v[52:55], v[166:169], v[186:189], 0
	v_mfma_f32_16x16x32_bf16 v[48:51], v[174:177], v[186:189], 0
	v_mfma_f32_16x16x32_bf16 v[36:39], v[166:169], v[194:197], 0
	v_mfma_f32_16x16x32_bf16 v[32:35], v[174:177], v[194:197], 0
	v_mfma_f32_16x16x32_bf16 v[20:23], v[166:169], v[202:205], 0
	v_mfma_f32_16x16x32_bf16 v[16:19], v[174:177], v[202:205], 0
	v_mfma_f32_16x16x32_bf16 v[4:7], v[166:169], v[210:213], 0
	v_mfma_f32_16x16x32_bf16 v[0:3], v[174:177], v[210:213], 0
	v_mfma_f32_16x16x32_bf16 v[52:55], v[170:173], v[190:193], v[52:55]
	v_mfma_f32_16x16x32_bf16 v[48:51], v[178:181], v[190:193], v[48:51]
	v_mfma_f32_16x16x32_bf16 v[36:39], v[170:173], v[198:201], v[36:39]
	v_mfma_f32_16x16x32_bf16 v[32:35], v[178:181], v[198:201], v[32:35]
	v_mfma_f32_16x16x32_bf16 v[20:23], v[170:173], v[206:209], v[20:23]
	v_mfma_f32_16x16x32_bf16 v[16:19], v[178:181], v[206:209], v[16:19]
	v_mfma_f32_16x16x32_bf16 v[4:7], v[170:173], v[214:217], v[4:7]
	v_mfma_f32_16x16x32_bf16 v[0:3], v[178:181], v[214:217], v[0:3]
	s_setprio 0
	s_barrier
	s_add_i32 s62, 0, 0x18000
	s_add_i32 s63, 0, 0x1c000
	v_add_u32_e32 v162, s62, v149
	v_add_u32_e32 v178, s63, v149
	ds_read_b128 v[144:147], v162
	ds_read_b128 v[154:157], v162 offset:1024
	ds_read_b128 v[158:161], v162 offset:2048
	ds_read_b128 v[162:165], v162 offset:3072
	ds_read_b128 v[166:169], v178
	ds_read_b128 v[170:173], v178 offset:1024
	ds_read_b128 v[174:177], v178 offset:2048
	ds_read_b128 v[178:181], v178 offset:3072
	s_add_u32 s46, s46, s16
	s_addc_u32 s47, s47, s17
	s_mov_b32 m0, s3
	s_nop 0
	global_load_lds_dwordx4 v[230:231], off
	s_mov_b32 m0, s28
	s_nop 0
	global_load_lds_dwordx4 v[232:233], off
	s_mov_b32 m0, s33
	v_lshl_add_u64 v[234:235], s[46:47], 0, v[128:129]
	ds_read_b128 v[186:189], v153 offset:32768
	ds_read_b128 v[190:193], v153 offset:33792
	ds_read_b128 v[194:197], v153 offset:34816
	ds_read_b128 v[198:201], v153 offset:35840
	ds_read_b128 v[202:205], v153 offset:36864
	ds_read_b128 v[206:209], v153 offset:37888
	ds_read_b128 v[210:213], v153 offset:38912
	ds_read_b128 v[214:217], v153 offset:39936
	global_load_lds_dwordx4 v[234:235], off
	v_lshl_add_u64 v[234:235], s[46:47], 0, v[132:133]
	s_mov_b32 m0, s48
	s_nop 0
	global_load_lds_dwordx4 v[234:235], off
	s_waitcnt vmcnt(8)
	s_waitcnt lgkmcnt(0)
	s_barrier
	s_setprio 1
	s_waitcnt lgkmcnt(0)
	v_mfma_f32_16x16x32_bf16 v[124:127], v[144:147], v[186:189], v[124:127]
	v_mfma_f32_16x16x32_bf16 v[120:123], v[158:161], v[186:189], v[120:123]
	v_mfma_f32_16x16x32_bf16 v[108:111], v[144:147], v[194:197], v[108:111]
	v_mfma_f32_16x16x32_bf16 v[104:107], v[158:161], v[194:197], v[104:107]
	v_mfma_f32_16x16x32_bf16 v[92:95], v[144:147], v[202:205], v[92:95]
	v_mfma_f32_16x16x32_bf16 v[88:91], v[158:161], v[202:205], v[88:91]
	v_mfma_f32_16x16x32_bf16 v[76:79], v[144:147], v[210:213], v[76:79]
	v_mfma_f32_16x16x32_bf16 v[72:75], v[158:161], v[210:213], v[72:75]
	v_mfma_f32_16x16x32_bf16 v[124:127], v[154:157], v[190:193], v[124:127]
	v_mfma_f32_16x16x32_bf16 v[120:123], v[162:165], v[190:193], v[120:123]
	v_mfma_f32_16x16x32_bf16 v[108:111], v[154:157], v[198:201], v[108:111]
	v_mfma_f32_16x16x32_bf16 v[104:107], v[162:165], v[198:201], v[104:107]
	v_mfma_f32_16x16x32_bf16 v[92:95], v[154:157], v[206:209], v[92:95]
	v_mfma_f32_16x16x32_bf16 v[88:91], v[162:165], v[206:209], v[88:91]
	v_mfma_f32_16x16x32_bf16 v[76:79], v[154:157], v[214:217], v[76:79]
	v_mfma_f32_16x16x32_bf16 v[72:75], v[162:165], v[214:217], v[72:75]
	s_setprio 0
	s_setprio 1
	v_mfma_f32_16x16x32_bf16 v[116:119], v[166:169], v[186:189], v[116:119]
	v_mfma_f32_16x16x32_bf16 v[112:115], v[174:177], v[186:189], v[112:115]
	v_mfma_f32_16x16x32_bf16 v[100:103], v[166:169], v[194:197], v[100:103]
	v_mfma_f32_16x16x32_bf16 v[96:99], v[174:177], v[194:197], v[96:99]
	v_mfma_f32_16x16x32_bf16 v[84:87], v[166:169], v[202:205], v[84:87]
	v_mfma_f32_16x16x32_bf16 v[80:83], v[174:177], v[202:205], v[80:83]
	v_mfma_f32_16x16x32_bf16 v[68:71], v[166:169], v[210:213], v[68:71]
	v_mfma_f32_16x16x32_bf16 v[64:67], v[174:177], v[210:213], v[64:67]
	v_mfma_f32_16x16x32_bf16 v[116:119], v[170:173], v[190:193], v[116:119]
	v_mfma_f32_16x16x32_bf16 v[112:115], v[178:181], v[190:193], v[112:115]
	v_mfma_f32_16x16x32_bf16 v[100:103], v[170:173], v[198:201], v[100:103]
	v_mfma_f32_16x16x32_bf16 v[96:99], v[178:181], v[198:201], v[96:99]
	v_mfma_f32_16x16x32_bf16 v[84:87], v[170:173], v[206:209], v[84:87]
	v_mfma_f32_16x16x32_bf16 v[80:83], v[178:181], v[206:209], v[80:83]
	v_mfma_f32_16x16x32_bf16 v[68:71], v[170:173], v[214:217], v[68:71]
	v_mfma_f32_16x16x32_bf16 v[64:67], v[178:181], v[214:217], v[64:67]
	s_setprio 0
	s_barrier
	s_add_i32 s46, s62, s31
	v_lshl_add_u64 v[182:183], v[182:183], 0, s[40:41]
	s_mov_b32 m0, s46
	ds_read_b128 v[186:189], v153 offset:49152
	ds_read_b128 v[190:193], v153 offset:50176
	ds_read_b128 v[194:197], v153 offset:51200
	ds_read_b128 v[198:201], v153 offset:52224
	ds_read_b128 v[202:205], v153 offset:53248
	ds_read_b128 v[206:209], v153 offset:54272
	ds_read_b128 v[210:213], v153 offset:55296
	ds_read_b128 v[214:217], v153 offset:56320
	global_load_lds_dwordx4 v[182:183], off
	v_lshl_add_u64 v[182:183], v[224:225], 0, s[40:41]
	s_add_i32 m0, s46, 0x2000
	s_add_i32 s46, s63, s31
	global_load_lds_dwordx4 v[182:183], off
	v_lshl_add_u64 v[182:183], v[226:227], 0, s[40:41]
	s_mov_b32 m0, s46
	s_nop 0
	global_load_lds_dwordx4 v[182:183], off
	v_lshl_add_u64 v[182:183], v[228:229], 0, s[40:41]
	s_add_i32 m0, s46, 0x2000
	s_nop 0
	global_load_lds_dwordx4 v[182:183], off
	s_waitcnt vmcnt(6)
	s_waitcnt lgkmcnt(0)
	s_barrier
	s_setprio 1
	s_waitcnt lgkmcnt(0)
	v_mfma_f32_16x16x32_bf16 v[60:63], v[144:147], v[186:189], v[60:63]
	v_mfma_f32_16x16x32_bf16 v[56:59], v[158:161], v[186:189], v[56:59]
	v_mfma_f32_16x16x32_bf16 v[44:47], v[144:147], v[194:197], v[44:47]
	v_mfma_f32_16x16x32_bf16 v[40:43], v[158:161], v[194:197], v[40:43]
	v_mfma_f32_16x16x32_bf16 v[28:31], v[144:147], v[202:205], v[28:31]
	v_mfma_f32_16x16x32_bf16 v[24:27], v[158:161], v[202:205], v[24:27]
	v_mfma_f32_16x16x32_bf16 v[12:15], v[144:147], v[210:213], v[12:15]
	v_mfma_f32_16x16x32_bf16 v[8:11], v[158:161], v[210:213], v[8:11]
	v_mfma_f32_16x16x32_bf16 v[60:63], v[154:157], v[190:193], v[60:63]
	v_mfma_f32_16x16x32_bf16 v[56:59], v[162:165], v[190:193], v[56:59]
	v_mfma_f32_16x16x32_bf16 v[44:47], v[154:157], v[198:201], v[44:47]
	v_mfma_f32_16x16x32_bf16 v[40:43], v[162:165], v[198:201], v[40:43]
	v_mfma_f32_16x16x32_bf16 v[28:31], v[154:157], v[206:209], v[28:31]
	v_mfma_f32_16x16x32_bf16 v[24:27], v[162:165], v[206:209], v[24:27]
	v_mfma_f32_16x16x32_bf16 v[12:15], v[154:157], v[214:217], v[12:15]
	v_mfma_f32_16x16x32_bf16 v[8:11], v[162:165], v[214:217], v[8:11]
	s_setprio 0
	s_setprio 1
	v_mfma_f32_16x16x32_bf16 v[52:55], v[166:169], v[186:189], v[52:55]
	v_mfma_f32_16x16x32_bf16 v[48:51], v[174:177], v[186:189], v[48:51]
	v_mfma_f32_16x16x32_bf16 v[36:39], v[166:169], v[194:197], v[36:39]
	v_mfma_f32_16x16x32_bf16 v[32:35], v[174:177], v[194:197], v[32:35]
	v_mfma_f32_16x16x32_bf16 v[20:23], v[166:169], v[202:205], v[20:23]
	v_mfma_f32_16x16x32_bf16 v[16:19], v[174:177], v[202:205], v[16:19]
	v_mfma_f32_16x16x32_bf16 v[4:7], v[166:169], v[210:213], v[4:7]
	v_mfma_f32_16x16x32_bf16 v[0:3], v[174:177], v[210:213], v[0:3]
	v_mfma_f32_16x16x32_bf16 v[52:55], v[170:173], v[190:193], v[52:55]
	v_mfma_f32_16x16x32_bf16 v[48:51], v[178:181], v[190:193], v[48:51]
	v_mfma_f32_16x16x32_bf16 v[36:39], v[170:173], v[198:201], v[36:39]
	v_mfma_f32_16x16x32_bf16 v[32:35], v[178:181], v[198:201], v[32:35]
	v_mfma_f32_16x16x32_bf16 v[20:23], v[170:173], v[206:209], v[20:23]
	v_mfma_f32_16x16x32_bf16 v[16:19], v[178:181], v[206:209], v[16:19]
	v_mfma_f32_16x16x32_bf16 v[4:7], v[170:173], v[214:217], v[4:7]
	v_mfma_f32_16x16x32_bf16 v[0:3], v[178:181], v[214:217], v[0:3]
	s_setprio 0
	s_barrier
	s_add_u32 s44, s44, 0x100
	s_addc_u32 s45, s45, 0
	s_add_u32 s59, s59, 0x100
	s_addc_u32 s60, s60, 0
	s_cmp_ge_i32 s61, s51
	s_mov_b32 s46, s61
	s_cbranch_scc1 .LBB0_1004

.LBB0_1004:
	v_lshl_add_u64 v[182:183], v[230:231], 0, s[40:41]
	s_mov_b32 m0, s49
	s_nop 0
	global_load_lds_dwordx4 v[182:183], off
	v_lshl_add_u64 v[182:183], v[232:233], 0, s[40:41]
	s_mov_b32 m0, s50
	s_nop 0
	global_load_lds_dwordx4 v[182:183], off
	v_lshl_add_u32 v146, s58, 8, v148
	v_lshl_add_u32 v144, s36, 8, v150
	v_lshlrev_b32_e32 v144, 1, v144
	v_lshl_add_u32 v162, v146, 11, v144
	global_load_dwordx4 v[186:189], v162, s[34:35]
	global_load_dwordx4 v[190:193], v162, s[34:35] offset:256
	v_add_u32_e32 v163, 0x8000, v162
	global_load_dwordx4 v[194:197], v163, s[34:35]
	global_load_dwordx4 v[198:201], v163, s[34:35] offset:256
	v_add_u32_e32 v163, 0x10000, v162
	global_load_dwordx4 v[202:205], v163, s[34:35]
	global_load_dwordx4 v[206:209], v163, s[34:35] offset:256
	v_add_u32_e32 v163, 0x18000, v162
	global_load_dwordx4 v[210:213], v163, s[34:35]
	global_load_dwordx4 v[214:217], v163, s[34:35] offset:256
	v_add_u32_e32 v163, 0x40000, v162
	global_load_dwordx4 v[224:227], v163, s[34:35]
	global_load_dwordx4 v[236:239], v163, s[34:35] offset:256
	v_add_u32_e32 v163, 0x48000, v162
	global_load_dwordx4 v[240:243], v163, s[34:35]
	global_load_dwordx4 v[244:247], v163, s[34:35] offset:256
	v_add_u32_e32 v163, 0x50000, v162
	global_load_dwordx4 v[154:157], v163, s[34:35]
	global_load_dwordx4 v[158:161], v163, s[34:35] offset:256
	v_add_u32_e32 v163, 0x58000, v162
	global_load_dwordx4 v[164:167], v163, s[34:35]
	global_load_dwordx4 v[250:253], v163, s[34:35] offset:256
	s_and_b64 vcc, exec, s[94:95]
	s_cbranch_vccz .LBB0_1006
	s_barrier

.LBB0_1110:
	s_andn2_b64 vcc, exec, s[38:39]
	s_cbranch_vccnz .Lzx1112
	s_add_u32 s4, s48, 0x80
	s_addc_u32 s5, s49, 0
	s_add_u32 s33, s46, 0x100
	s_addc_u32 s48, s47, 0
	s_mov_b32 s46, 0
	ds_read_b128 v[144:147], v151
	ds_read_b128 v[156:159], v151 offset:1024
	ds_read_b128 v[160:163], v151 offset:2048
	ds_read_b128 v[164:167], v151 offset:3072
	ds_read_b128 v[168:171], v152
	ds_read_b128 v[172:175], v152 offset:1024
	ds_read_b128 v[176:179], v152 offset:2048
	ds_read_b128 v[180:183], v152 offset:3072
	s_add_i32 s49, s46, 2
	s_add_u32 s52, s4, 0x80
	s_addc_u32 s47, s5, 0
	s_cmp_eq_u32 s60, s46
	s_cselect_b32 s46, s42, s52
	s_cselect_b32 s47, s43, s47
	s_cselect_b32 s53, s45, s48
	s_cselect_b32 s52, s44, s33
	v_lshl_add_u64 v[224:225], s[4:5], 0, v[136:137]
	s_add_i32 m0, s50, 0xc000
	ds_read_b128 v[186:189], v153
	ds_read_b128 v[190:193], v153 offset:1024
	ds_read_b128 v[194:197], v153 offset:2048
	ds_read_b128 v[198:201], v153 offset:3072
	ds_read_b128 v[202:205], v153 offset:4096
	ds_read_b128 v[206:209], v153 offset:5120
	ds_read_b128 v[210:213], v153 offset:6144
	ds_read_b128 v[214:217], v153 offset:7168
	global_load_lds_dwordx4 v[224:225], off
	v_lshl_add_u64 v[224:225], s[4:5], 0, v[138:139]
	s_add_i32 m0, s50, 0xe000
	s_nop 0
	global_load_lds_dwordx4 v[224:225], off
	s_waitcnt vmcnt(8)
	s_waitcnt lgkmcnt(0)
	s_barrier
	s_setprio 1
	s_waitcnt lgkmcnt(0)
	v_mfma_f32_16x16x32_bf16 v[124:127], v[144:147], v[186:189], 0
	v_mfma_f32_16x16x32_bf16 v[120:123], v[160:163], v[186:189], 0
	v_mfma_f32_16x16x32_bf16 v[108:111], v[144:147], v[194:197], 0
	v_mfma_f32_16x16x32_bf16 v[104:107], v[160:163], v[194:197], 0
	v_mfma_f32_16x16x32_bf16 v[92:95], v[144:147], v[202:205], 0
	v_mfma_f32_16x16x32_bf16 v[88:91], v[160:163], v[202:205], 0
	v_mfma_f32_16x16x32_bf16 v[76:79], v[144:147], v[210:213], 0
	v_mfma_f32_16x16x32_bf16 v[72:75], v[160:163], v[210:213], 0
	v_mfma_f32_16x16x32_bf16 v[124:127], v[156:159], v[190:193], v[124:127]
	v_mfma_f32_16x16x32_bf16 v[120:123], v[164:167], v[190:193], v[120:123]
	v_mfma_f32_16x16x32_bf16 v[108:111], v[156:159], v[198:201], v[108:111]
	v_mfma_f32_16x16x32_bf16 v[104:107], v[164:167], v[198:201], v[104:107]
	v_mfma_f32_16x16x32_bf16 v[92:95], v[156:159], v[206:209], v[92:95]
	v_mfma_f32_16x16x32_bf16 v[88:91], v[164:167], v[206:209], v[88:91]
	v_mfma_f32_16x16x32_bf16 v[76:79], v[156:159], v[214:217], v[76:79]
	v_mfma_f32_16x16x32_bf16 v[72:75], v[164:167], v[214:217], v[72:75]
	s_setprio 0
	s_setprio 1
	v_mfma_f32_16x16x32_bf16 v[116:119], v[168:171], v[186:189], 0
	v_mfma_f32_16x16x32_bf16 v[112:115], v[176:179], v[186:189], 0
	v_mfma_f32_16x16x32_bf16 v[100:103], v[168:171], v[194:197], 0
	v_mfma_f32_16x16x32_bf16 v[96:99], v[176:179], v[194:197], 0
	v_mfma_f32_16x16x32_bf16 v[84:87], v[168:171], v[202:205], 0
	v_mfma_f32_16x16x32_bf16 v[80:83], v[176:179], v[202:205], 0
	v_mfma_f32_16x16x32_bf16 v[68:71], v[168:171], v[210:213], 0
	v_mfma_f32_16x16x32_bf16 v[64:67], v[176:179], v[210:213], 0
	v_mfma_f32_16x16x32_bf16 v[116:119], v[172:175], v[190:193], v[116:119]
	v_mfma_f32_16x16x32_bf16 v[112:115], v[180:183], v[190:193], v[112:115]
	v_mfma_f32_16x16x32_bf16 v[100:103], v[172:175], v[198:201], v[100:103]
	v_mfma_f32_16x16x32_bf16 v[96:99], v[180:183], v[198:201], v[96:99]
	v_mfma_f32_16x16x32_bf16 v[84:87], v[172:175], v[206:209], v[84:87]
	v_mfma_f32_16x16x32_bf16 v[80:83], v[180:183], v[206:209], v[80:83]
	v_mfma_f32_16x16x32_bf16 v[68:71], v[172:175], v[214:217], v[68:71]
	v_mfma_f32_16x16x32_bf16 v[64:67], v[180:183], v[214:217], v[64:67]
	s_setprio 0
	s_barrier
	s_add_i32 s65, s61, s31
	v_lshl_add_u64 v[224:225], s[52:53], 0, v[130:131]
	s_mov_b32 m0, s65
	ds_read_b128 v[186:189], v153 offset:16384
	ds_read_b128 v[190:193], v153 offset:17408
	ds_read_b128 v[194:197], v153 offset:18432
	ds_read_b128 v[198:201], v153 offset:19456
	ds_read_b128 v[202:205], v153 offset:20480
	ds_read_b128 v[206:209], v153 offset:21504
	ds_read_b128 v[210:213], v153 offset:22528
	ds_read_b128 v[214:217], v153 offset:23552
	global_load_lds_dwordx4 v[224:225], off
	s_add_i32 m0, s65, 0x2000
	v_lshl_add_u64 v[226:227], s[52:53], 0, v[134:135]
	s_add_u32 s52, s52, s14
	s_addc_u32 s53, s53, s15
	s_add_i32 s65, s62, s31
	global_load_lds_dwordx4 v[226:227], off
	v_lshl_add_u64 v[228:229], s[52:53], 0, v[130:131]
	s_mov_b32 m0, s65
	v_lshl_add_u64 v[230:231], s[52:53], 0, v[134:135]
	global_load_lds_dwordx4 v[228:229], off
	s_add_i32 m0, s65, 0x2000
	v_lshl_add_u64 v[232:233], s[46:47], 0, v[128:129]
	global_load_lds_dwordx4 v[230:231], off
	v_lshl_add_u64 v[234:235], s[46:47], 0, v[132:133]
	s_waitcnt vmcnt(6)
	s_waitcnt lgkmcnt(0)
	s_barrier
	s_setprio 1
	s_waitcnt lgkmcnt(0)
	v_mfma_f32_16x16x32_bf16 v[60:63], v[144:147], v[186:189], 0
	v_mfma_f32_16x16x32_bf16 v[56:59], v[160:163], v[186:189], 0
	v_mfma_f32_16x16x32_bf16 v[44:47], v[144:147], v[194:197], 0
	v_mfma_f32_16x16x32_bf16 v[40:43], v[160:163], v[194:197], 0
	v_mfma_f32_16x16x32_bf16 v[28:31], v[144:147], v[202:205], 0
	v_mfma_f32_16x16x32_bf16 v[24:27], v[160:163], v[202:205], 0
	v_mfma_f32_16x16x32_bf16 v[12:15], v[144:147], v[210:213], 0
	v_mfma_f32_16x16x32_bf16 v[8:11], v[160:163], v[210:213], 0
	v_mfma_f32_16x16x32_bf16 v[60:63], v[156:159], v[190:193], v[60:63]
	v_mfma_f32_16x16x32_bf16 v[56:59], v[164:167], v[190:193], v[56:59]
	v_mfma_f32_16x16x32_bf16 v[44:47], v[156:159], v[198:201], v[44:47]
	v_mfma_f32_16x16x32_bf16 v[40:43], v[164:167], v[198:201], v[40:43]
	v_mfma_f32_16x16x32_bf16 v[28:31], v[156:159], v[206:209], v[28:31]
	v_mfma_f32_16x16x32_bf16 v[24:27], v[164:167], v[206:209], v[24:27]
	v_mfma_f32_16x16x32_bf16 v[12:15], v[156:159], v[214:217], v[12:15]
	v_mfma_f32_16x16x32_bf16 v[8:11], v[164:167], v[214:217], v[8:11]
	s_setprio 0
	s_setprio 1
	v_mfma_f32_16x16x32_bf16 v[52:55], v[168:171], v[186:189], 0
	v_mfma_f32_16x16x32_bf16 v[48:51], v[176:179], v[186:189], 0
	v_mfma_f32_16x16x32_bf16 v[36:39], v[168:171], v[194:197], 0
	v_mfma_f32_16x16x32_bf16 v[32:35], v[176:179], v[194:197], 0
	v_mfma_f32_16x16x32_bf16 v[20:23], v[168:171], v[202:205], 0
	v_mfma_f32_16x16x32_bf16 v[16:19], v[176:179], v[202:205], 0
	v_mfma_f32_16x16x32_bf16 v[4:7], v[168:171], v[210:213], 0
	v_mfma_f32_16x16x32_bf16 v[0:3], v[176:179], v[210:213], 0
	v_mfma_f32_16x16x32_bf16 v[52:55], v[172:175], v[190:193], v[52:55]
	v_mfma_f32_16x16x32_bf16 v[48:51], v[180:183], v[190:193], v[48:51]
	v_mfma_f32_16x16x32_bf16 v[36:39], v[172:175], v[198:201], v[36:39]
	v_mfma_f32_16x16x32_bf16 v[32:35], v[180:183], v[198:201], v[32:35]
	v_mfma_f32_16x16x32_bf16 v[20:23], v[172:175], v[206:209], v[20:23]
	v_mfma_f32_16x16x32_bf16 v[16:19], v[180:183], v[206:209], v[16:19]
	v_mfma_f32_16x16x32_bf16 v[4:7], v[172:175], v[214:217], v[4:7]
	v_mfma_f32_16x16x32_bf16 v[0:3], v[180:183], v[214:217], v[0:3]
	s_setprio 0
	s_barrier
	s_add_i32 s52, 0, 0x18000
	v_add_u32_e32 v155, s52, v149
	s_add_i32 s53, 0, 0x1c000
	ds_read_b128 v[144:147], v155
	ds_read_b128 v[156:159], v155 offset:1024
	ds_read_b128 v[160:163], v155 offset:2048
	ds_read_b128 v[164:167], v155 offset:3072
	v_add_u32_e32 v155, s53, v149
	ds_read_b128 v[168:171], v155
	ds_read_b128 v[172:175], v155 offset:1024
	ds_read_b128 v[176:179], v155 offset:2048
	ds_read_b128 v[180:183], v155 offset:3072
	s_add_u32 s46, s46, s14
	s_addc_u32 s47, s47, s15
	s_mov_b32 m0, s50
	s_nop 0
	global_load_lds_dwordx4 v[232:233], off
	s_mov_b32 m0, s51
	s_nop 0
	global_load_lds_dwordx4 v[234:235], off
	s_mov_b32 m0, s54
	v_lshl_add_u64 v[236:237], s[46:47], 0, v[128:129]
	ds_read_b128 v[186:189], v153 offset:32768
	ds_read_b128 v[190:193], v153 offset:33792
	ds_read_b128 v[194:197], v153 offset:34816
	ds_read_b128 v[198:201], v153 offset:35840
	ds_read_b128 v[202:205], v153 offset:36864
	ds_read_b128 v[206:209], v153 offset:37888
	ds_read_b128 v[210:213], v153 offset:38912
	ds_read_b128 v[214:217], v153 offset:39936
	global_load_lds_dwordx4 v[236:237], off
	v_lshl_add_u64 v[236:237], s[46:47], 0, v[132:133]
	s_mov_b32 m0, s55
	s_nop 0
	global_load_lds_dwordx4 v[236:237], off
	s_waitcnt vmcnt(8)
	s_waitcnt lgkmcnt(0)
	s_barrier
	s_setprio 1
	s_waitcnt lgkmcnt(0)
	v_mfma_f32_16x16x32_bf16 v[124:127], v[144:147], v[186:189], v[124:127]
	v_mfma_f32_16x16x32_bf16 v[120:123], v[160:163], v[186:189], v[120:123]
	v_mfma_f32_16x16x32_bf16 v[108:111], v[144:147], v[194:197], v[108:111]
	v_mfma_f32_16x16x32_bf16 v[104:107], v[160:163], v[194:197], v[104:107]
	v_mfma_f32_16x16x32_bf16 v[92:95], v[144:147], v[202:205], v[92:95]
	v_mfma_f32_16x16x32_bf16 v[88:91], v[160:163], v[202:205], v[88:91]
	v_mfma_f32_16x16x32_bf16 v[76:79], v[144:147], v[210:213], v[76:79]
	v_mfma_f32_16x16x32_bf16 v[72:75], v[160:163], v[210:213], v[72:75]
	v_mfma_f32_16x16x32_bf16 v[124:127], v[156:159], v[190:193], v[124:127]
	v_mfma_f32_16x16x32_bf16 v[120:123], v[164:167], v[190:193], v[120:123]
	v_mfma_f32_16x16x32_bf16 v[108:111], v[156:159], v[198:201], v[108:111]
	v_mfma_f32_16x16x32_bf16 v[104:107], v[164:167], v[198:201], v[104:107]
	v_mfma_f32_16x16x32_bf16 v[92:95], v[156:159], v[206:209], v[92:95]
	v_mfma_f32_16x16x32_bf16 v[88:91], v[164:167], v[206:209], v[88:91]
	v_mfma_f32_16x16x32_bf16 v[76:79], v[156:159], v[214:217], v[76:79]
	v_mfma_f32_16x16x32_bf16 v[72:75], v[164:167], v[214:217], v[72:75]
	s_setprio 0
	s_setprio 1
	v_mfma_f32_16x16x32_bf16 v[116:119], v[168:171], v[186:189], v[116:119]
	v_mfma_f32_16x16x32_bf16 v[112:115], v[176:179], v[186:189], v[112:115]
	v_mfma_f32_16x16x32_bf16 v[100:103], v[168:171], v[194:197], v[100:103]
	v_mfma_f32_16x16x32_bf16 v[96:99], v[176:179], v[194:197], v[96:99]
	v_mfma_f32_16x16x32_bf16 v[84:87], v[168:171], v[202:205], v[84:87]
	v_mfma_f32_16x16x32_bf16 v[80:83], v[176:179], v[202:205], v[80:83]
	v_mfma_f32_16x16x32_bf16 v[68:71], v[168:171], v[210:213], v[68:71]
	v_mfma_f32_16x16x32_bf16 v[64:67], v[176:179], v[210:213], v[64:67]
	v_mfma_f32_16x16x32_bf16 v[116:119], v[172:175], v[190:193], v[116:119]
	v_mfma_f32_16x16x32_bf16 v[112:115], v[180:183], v[190:193], v[112:115]
	v_mfma_f32_16x16x32_bf16 v[100:103], v[172:175], v[198:201], v[100:103]
	v_mfma_f32_16x16x32_bf16 v[96:99], v[180:183], v[198:201], v[96:99]
	v_mfma_f32_16x16x32_bf16 v[84:87], v[172:175], v[206:209], v[84:87]
	v_mfma_f32_16x16x32_bf16 v[80:83], v[180:183], v[206:209], v[80:83]
	v_mfma_f32_16x16x32_bf16 v[68:71], v[172:175], v[214:217], v[68:71]
	v_mfma_f32_16x16x32_bf16 v[64:67], v[180:183], v[214:217], v[64:67]
	s_setprio 0
	s_barrier
	s_add_i32 s46, s52, s31
	v_lshl_add_u64 v[224:225], v[224:225], 0, s[36:37]
	s_mov_b32 m0, s46
	ds_read_b128 v[186:189], v153 offset:49152
	ds_read_b128 v[190:193], v153 offset:50176
	ds_read_b128 v[194:197], v153 offset:51200
	ds_read_b128 v[198:201], v153 offset:52224
	ds_read_b128 v[202:205], v153 offset:53248
	ds_read_b128 v[206:209], v153 offset:54272
	ds_read_b128 v[210:213], v153 offset:55296
	ds_read_b128 v[214:217], v153 offset:56320
	global_load_lds_dwordx4 v[224:225], off
	v_lshl_add_u64 v[224:225], v[226:227], 0, s[36:37]
	s_add_i32 m0, s46, 0x2000
	s_add_i32 s46, s53, s31
	global_load_lds_dwordx4 v[224:225], off
	v_lshl_add_u64 v[224:225], v[228:229], 0, s[36:37]
	s_mov_b32 m0, s46
	s_nop 0
	global_load_lds_dwordx4 v[224:225], off
	v_lshl_add_u64 v[224:225], v[230:231], 0, s[36:37]
	s_add_i32 m0, s46, 0x2000
	s_nop 0
	global_load_lds_dwordx4 v[224:225], off
	s_waitcnt vmcnt(6)
	s_waitcnt lgkmcnt(0)
	s_barrier
	s_setprio 1
	s_waitcnt lgkmcnt(0)
	v_mfma_f32_16x16x32_bf16 v[60:63], v[144:147], v[186:189], v[60:63]
	v_mfma_f32_16x16x32_bf16 v[56:59], v[160:163], v[186:189], v[56:59]
	v_mfma_f32_16x16x32_bf16 v[44:47], v[144:147], v[194:197], v[44:47]
	v_mfma_f32_16x16x32_bf16 v[40:43], v[160:163], v[194:197], v[40:43]
	v_mfma_f32_16x16x32_bf16 v[28:31], v[144:147], v[202:205], v[28:31]
	v_mfma_f32_16x16x32_bf16 v[24:27], v[160:163], v[202:205], v[24:27]
	v_mfma_f32_16x16x32_bf16 v[12:15], v[144:147], v[210:213], v[12:15]
	v_mfma_f32_16x16x32_bf16 v[8:11], v[160:163], v[210:213], v[8:11]
	v_mfma_f32_16x16x32_bf16 v[60:63], v[156:159], v[190:193], v[60:63]
	v_mfma_f32_16x16x32_bf16 v[56:59], v[164:167], v[190:193], v[56:59]
	v_mfma_f32_16x16x32_bf16 v[44:47], v[156:159], v[198:201], v[44:47]
	v_mfma_f32_16x16x32_bf16 v[40:43], v[164:167], v[198:201], v[40:43]
	v_mfma_f32_16x16x32_bf16 v[28:31], v[156:159], v[206:209], v[28:31]
	v_mfma_f32_16x16x32_bf16 v[24:27], v[164:167], v[206:209], v[24:27]
	v_mfma_f32_16x16x32_bf16 v[12:15], v[156:159], v[214:217], v[12:15]
	v_mfma_f32_16x16x32_bf16 v[8:11], v[164:167], v[214:217], v[8:11]
	s_setprio 0
	s_setprio 1
	v_mfma_f32_16x16x32_bf16 v[52:55], v[168:171], v[186:189], v[52:55]
	v_mfma_f32_16x16x32_bf16 v[48:51], v[176:179], v[186:189], v[48:51]
	v_mfma_f32_16x16x32_bf16 v[36:39], v[168:171], v[194:197], v[36:39]
	v_mfma_f32_16x16x32_bf16 v[32:35], v[176:179], v[194:197], v[32:35]
	v_mfma_f32_16x16x32_bf16 v[20:23], v[168:171], v[202:205], v[20:23]
	v_mfma_f32_16x16x32_bf16 v[16:19], v[176:179], v[202:205], v[16:19]
	v_mfma_f32_16x16x32_bf16 v[4:7], v[168:171], v[210:213], v[4:7]
	v_mfma_f32_16x16x32_bf16 v[0:3], v[176:179], v[210:213], v[0:3]
	v_mfma_f32_16x16x32_bf16 v[52:55], v[172:175], v[190:193], v[52:55]
	v_mfma_f32_16x16x32_bf16 v[48:51], v[180:183], v[190:193], v[48:51]
	v_mfma_f32_16x16x32_bf16 v[36:39], v[172:175], v[198:201], v[36:39]
	v_mfma_f32_16x16x32_bf16 v[32:35], v[180:183], v[198:201], v[32:35]
	v_mfma_f32_16x16x32_bf16 v[20:23], v[172:175], v[206:209], v[20:23]
	v_mfma_f32_16x16x32_bf16 v[16:19], v[180:183], v[206:209], v[16:19]
	v_mfma_f32_16x16x32_bf16 v[4:7], v[172:175], v[214:217], v[4:7]
	v_mfma_f32_16x16x32_bf16 v[0:3], v[180:183], v[214:217], v[0:3]
	s_setprio 0
	s_barrier
	s_add_u32 s4, s4, 0x100
	s_addc_u32 s5, s5, 0
	s_add_u32 s33, s33, 0x100
	s_addc_u32 s48, s48, 0
	s_cmp_ge_i32 s49, s59
	s_mov_b32 s46, s49
	s_cbranch_scc1 .LBB0_1113

.LBB0_1113:
	v_lshl_add_u64 v[224:225], v[232:233], 0, s[36:37]
	s_mov_b32 m0, s57
	s_nop 0
	global_load_lds_dwordx4 v[224:225], off
	v_lshl_add_u64 v[224:225], v[234:235], 0, s[36:37]
	s_mov_b32 m0, s58
	s_nop 0
	global_load_lds_dwordx4 v[224:225], off
	s_and_b64 vcc, exec, s[94:95]
	s_cbranch_vccz .LBB0_1115
	s_barrier
